# sub4 branch-pair epilogue: batched loads + counted vmcnt instead of 16 serialized load-wait-store rounds
# speedup vs baseline: 1.0015x; 1.0015x over previous
; __device__ __forceinline__ unsigned pk2(float lo, float hi) { f32x2 v = {lo, hi}; bf16x2_t b = __builtin_convertvector(v, bf16x2_t); return __builtin_bit_cast(unsigned, b); }
; __device__ __forceinline__ float sigm(float x) { return __builtin_amdgcn_rcpf(1.f + fexp(-x)); }
;     __device__ __forceinline__ void operator()(const f32x4 (&acc)[2][2][4][2], const Unit& u, int wr, int wc, int fr, int fq) const {
;     ...
;                 bf16_t* rowp = P + (size_t)(row0 + ai * HALF + m * 16) * LDP + col0; bf16_t* roww = W + (size_t)((row0 + ai * HALF + m * 16) & rmask) * LDP + col0;
; #pragma unroll
;                 for (int bj = 0; bj < 2; ++bj) {
;                     const u32x4 a = *(const u32x4*)(rowp + C_MA + bj * HALF);
;                     float ma[8] = {bflo(a.x), bfhi(a.x), bflo(a.y), bfhi(a.y), bflo(a.z), bfhi(a.z), bflo(a.w), bfhi(a.w)};
;                     float o[8];
;                     if (SECOND) {
;                         const u32x4 b = *(const u32x4*)(rowp + C_MB + bj * HALF);
;                         float mb[8] = {bflo(b.x), bfhi(b.x), bflo(b.y), bfhi(b.y), bflo(b.z), bfhi(b.z), bflo(b.w), bfhi(b.w)};
; #pragma unroll
;                         for (int e = 0; e < 8; ++e) o[e] = ma[e] + acc[ai][bj][m][e >> 2][e & 3] * sigm(mb[e]);
;                     } else {
; #pragma unroll
;                         for (int e = 0; e < 8; ++e) o[e] = acc[ai][bj][m][e >> 2][e & 3] * sigm(ma[e]);
;                     }
;                     u32x4 w; w.x = pk2(o[0], o[1]); w.y = pk2(o[2], o[3]); w.z = pk2(o[4], o[5]); w.w = pk2(o[6], o[7]);
;                     *(u32x4*)(roww + C_MA + bj * HALF) = w;
.LBB0_46:
	v_lshl_add_u32 v160, s18, 8, v156
	v_lshl_or_b32 v130, s19, 8, v158
	v_mul_u32_u24_e32 v216, s28, v160
	v_lshl_add_u32 v216, v130, 1, v216
	v_add_u32_e32 v216, 0x2c00, v216
	s_cmp_lg_u32 s25, 0
	s_cbranch_scc0 .Lbp_sel0
	global_load_dwordx4 v[160:163], v216, s[94:95] offset:2048
	global_load_dwordx4 v[164:167], v216, s[94:95] offset:2304
	v_add_u32_e32 v218, 0x3e000, v216
	global_load_dwordx4 v[168:171], v218, s[94:95] offset:2048
	global_load_dwordx4 v[172:175], v218, s[94:95] offset:2304
	v_add_u32_e32 v217, 0x7c000, v216
	global_load_dwordx4 v[176:179], v217, s[94:95] offset:2048
	global_load_dwordx4 v[180:183], v217, s[94:95] offset:2304
	v_add_u32_e32 v218, 0xba000, v216
	global_load_dwordx4 v[184:187], v218, s[94:95] offset:2048
	global_load_dwordx4 v[188:191], v218, s[94:95] offset:2304
	v_add_u32_e32 v217, 0x1f0000, v216
	global_load_dwordx4 v[192:195], v217, s[94:95] offset:2048
	global_load_dwordx4 v[196:199], v217, s[94:95] offset:2304
	v_add_u32_e32 v218, 0x22e000, v216
	global_load_dwordx4 v[200:203], v218, s[94:95] offset:2048
	global_load_dwordx4 v[204:207], v218, s[94:95] offset:2304
	v_add_u32_e32 v217, 0x26c000, v216
	global_load_dwordx4 v[130:133], v217, s[94:95] offset:2048
	global_load_dwordx4 v[134:137], v217, s[94:95] offset:2304
	v_add_u32_e32 v218, 0x2aa000, v216
	global_load_dwordx4 v[148:151], v218, s[94:95] offset:2048
	global_load_dwordx4 v[152:155], v218, s[94:95] offset:2304
	s_waitcnt vmcnt(15)
	v_lshlrev_b32_e32 v218, 16, v160
	v_and_b32_e32 v219, 0xffff0000, v160
	v_lshlrev_b32_e32 v220, 16, v161
	v_and_b32_e32 v221, 0xffff0000, v161
	v_lshlrev_b32_e32 v222, 16, v162
	v_and_b32_e32 v223, 0xffff0000, v162
	v_lshlrev_b32_e32 v224, 16, v163
	v_and_b32_e32 v225, 0xffff0000, v163
	v_mul_f32_e32 v218, 0xbfb8aa3b, v218
	v_mul_f32_e32 v219, 0xbfb8aa3b, v219
	v_mul_f32_e32 v220, 0xbfb8aa3b, v220
	v_mul_f32_e32 v221, 0xbfb8aa3b, v221
	v_mul_f32_e32 v222, 0xbfb8aa3b, v222
	v_mul_f32_e32 v223, 0xbfb8aa3b, v223
	v_mul_f32_e32 v224, 0xbfb8aa3b, v224
	v_mul_f32_e32 v225, 0xbfb8aa3b, v225
	v_exp_f32_e32 v218, v218
	v_exp_f32_e32 v219, v219
	v_exp_f32_e32 v220, v220
	v_exp_f32_e32 v221, v221
	v_exp_f32_e32 v222, v222
	v_exp_f32_e32 v223, v223
	v_exp_f32_e32 v224, v224
	v_exp_f32_e32 v225, v225
	v_add_f32_e32 v218, 1.0, v218
	v_add_f32_e32 v219, 1.0, v219
	v_add_f32_e32 v220, 1.0, v220
	v_add_f32_e32 v221, 1.0, v221
	v_add_f32_e32 v222, 1.0, v222
	v_add_f32_e32 v223, 1.0, v223
	v_add_f32_e32 v224, 1.0, v224
	v_add_f32_e32 v225, 1.0, v225
	v_rcp_f32_e32 v218, v218
	v_rcp_f32_e32 v219, v219
	v_rcp_f32_e32 v220, v220
	v_rcp_f32_e32 v221, v221
	v_rcp_f32_e32 v222, v222
	v_rcp_f32_e32 v223, v223
	v_rcp_f32_e32 v224, v224
	v_rcp_f32_e32 v225, v225
	v_pk_mul_f32 v[126:127], v[126:127], v[218:219]
	v_pk_mul_f32 v[128:129], v[128:129], v[220:221]
	v_pk_mul_f32 v[122:123], v[122:123], v[222:223]
	v_pk_mul_f32 v[124:125], v[124:125], v[224:225]
	global_load_dwordx4 v[160:163], v216, s[94:95]
	s_waitcnt vmcnt(15)
	v_lshlrev_b32_e32 v218, 16, v164
	v_and_b32_e32 v219, 0xffff0000, v164
	v_lshlrev_b32_e32 v220, 16, v165
	v_and_b32_e32 v221, 0xffff0000, v165
	v_lshlrev_b32_e32 v222, 16, v166
	v_and_b32_e32 v223, 0xffff0000, v166
	v_lshlrev_b32_e32 v224, 16, v167
	v_and_b32_e32 v225, 0xffff0000, v167
	v_mul_f32_e32 v218, 0xbfb8aa3b, v218
	v_mul_f32_e32 v219, 0xbfb8aa3b, v219
	v_mul_f32_e32 v220, 0xbfb8aa3b, v220
	v_mul_f32_e32 v221, 0xbfb8aa3b, v221
	v_mul_f32_e32 v222, 0xbfb8aa3b, v222
	v_mul_f32_e32 v223, 0xbfb8aa3b, v223
	v_mul_f32_e32 v224, 0xbfb8aa3b, v224
	v_mul_f32_e32 v225, 0xbfb8aa3b, v225
	v_exp_f32_e32 v218, v218
	v_exp_f32_e32 v219, v219
	v_exp_f32_e32 v220, v220
	v_exp_f32_e32 v221, v221
	v_exp_f32_e32 v222, v222
	v_exp_f32_e32 v223, v223
	v_exp_f32_e32 v224, v224
	v_exp_f32_e32 v225, v225
	v_add_f32_e32 v218, 1.0, v218
	v_add_f32_e32 v219, 1.0, v219
	v_add_f32_e32 v220, 1.0, v220
	v_add_f32_e32 v221, 1.0, v221
	v_add_f32_e32 v222, 1.0, v222
	v_add_f32_e32 v223, 1.0, v223
	v_add_f32_e32 v224, 1.0, v224
	v_add_f32_e32 v225, 1.0, v225
	v_rcp_f32_e32 v218, v218
	v_rcp_f32_e32 v219, v219
	v_rcp_f32_e32 v220, v220
	v_rcp_f32_e32 v221, v221
	v_rcp_f32_e32 v222, v222
	v_rcp_f32_e32 v223, v223
	v_rcp_f32_e32 v224, v224
	v_rcp_f32_e32 v225, v225
	v_pk_mul_f32 v[118:119], v[118:119], v[218:219]
	v_pk_mul_f32 v[120:121], v[120:121], v[220:221]
	v_pk_mul_f32 v[114:115], v[114:115], v[222:223]
	v_pk_mul_f32 v[116:117], v[116:117], v[224:225]
	global_load_dwordx4 v[164:167], v216, s[94:95] offset:256
	s_waitcnt vmcnt(15)
	v_lshlrev_b32_e32 v218, 16, v168
	v_and_b32_e32 v219, 0xffff0000, v168
	v_lshlrev_b32_e32 v220, 16, v169
	v_and_b32_e32 v221, 0xffff0000, v169
	v_lshlrev_b32_e32 v222, 16, v170
	v_and_b32_e32 v223, 0xffff0000, v170
	v_lshlrev_b32_e32 v224, 16, v171
	v_and_b32_e32 v225, 0xffff0000, v171
	v_mul_f32_e32 v218, 0xbfb8aa3b, v218
	v_mul_f32_e32 v219, 0xbfb8aa3b, v219
	v_mul_f32_e32 v220, 0xbfb8aa3b, v220
	v_mul_f32_e32 v221, 0xbfb8aa3b, v221
	v_mul_f32_e32 v222, 0xbfb8aa3b, v222
	v_mul_f32_e32 v223, 0xbfb8aa3b, v223
	v_mul_f32_e32 v224, 0xbfb8aa3b, v224
	v_mul_f32_e32 v225, 0xbfb8aa3b, v225
	v_exp_f32_e32 v218, v218
	v_exp_f32_e32 v219, v219
	v_exp_f32_e32 v220, v220
	v_exp_f32_e32 v221, v221
	v_exp_f32_e32 v222, v222
	v_exp_f32_e32 v223, v223
	v_exp_f32_e32 v224, v224
	v_exp_f32_e32 v225, v225
	v_add_f32_e32 v218, 1.0, v218
	v_add_f32_e32 v219, 1.0, v219
	v_add_f32_e32 v220, 1.0, v220
	v_add_f32_e32 v221, 1.0, v221
	v_add_f32_e32 v222, 1.0, v222
	v_add_f32_e32 v223, 1.0, v223
	v_add_f32_e32 v224, 1.0, v224
	v_add_f32_e32 v225, 1.0, v225
	v_rcp_f32_e32 v218, v218
	v_rcp_f32_e32 v219, v219
	v_rcp_f32_e32 v220, v220
	v_rcp_f32_e32 v221, v221
	v_rcp_f32_e32 v222, v222
	v_rcp_f32_e32 v223, v223
	v_rcp_f32_e32 v224, v224
	v_rcp_f32_e32 v225, v225
	v_pk_mul_f32 v[110:111], v[110:111], v[218:219]
	v_pk_mul_f32 v[112:113], v[112:113], v[220:221]
	v_pk_mul_f32 v[106:107], v[106:107], v[222:223]
	v_pk_mul_f32 v[108:109], v[108:109], v[224:225]
	v_add_u32_e32 v217, 0x3e000, v216
	global_load_dwordx4 v[168:171], v217, s[94:95]
	s_waitcnt vmcnt(15)
; __device__ __forceinline__ float sigm(float x) { return __builtin_amdgcn_rcpf(1.f + fexp(-x)); }
;     __device__ __forceinline__ void operator()(const f32x4 (&acc)[2][2][4][2], const Unit& u, int wr, int wc, int fr, int fq) const {
;     ...
;                         const u32x4 b = *(const u32x4*)(rowp + C_MB + bj * HALF);
;                         float mb[8] = {bflo(b.x), bfhi(b.x), bflo(b.y), bfhi(b.y), bflo(b.z), bfhi(b.z), bflo(b.w), bfhi(b.w)};
; #pragma unroll
;                         for (int e = 0; e < 8; ++e) o[e] = ma[e] + acc[ai][bj][m][e >> 2][e & 3] * sigm(mb[e]);
	v_lshlrev_b32_e32 v218, 16, v172
	v_and_b32_e32 v219, 0xffff0000, v172
	v_lshlrev_b32_e32 v220, 16, v173
	v_and_b32_e32 v221, 0xffff0000, v173
	v_lshlrev_b32_e32 v222, 16, v174
	v_and_b32_e32 v223, 0xffff0000, v174
	v_lshlrev_b32_e32 v224, 16, v175
	v_and_b32_e32 v225, 0xffff0000, v175
	v_mul_f32_e32 v218, 0xbfb8aa3b, v218
	v_mul_f32_e32 v219, 0xbfb8aa3b, v219
	v_mul_f32_e32 v220, 0xbfb8aa3b, v220
	v_mul_f32_e32 v221, 0xbfb8aa3b, v221
	v_mul_f32_e32 v222, 0xbfb8aa3b, v222
	v_mul_f32_e32 v223, 0xbfb8aa3b, v223
	v_mul_f32_e32 v224, 0xbfb8aa3b, v224
	v_mul_f32_e32 v225, 0xbfb8aa3b, v225
	v_exp_f32_e32 v218, v218
	v_exp_f32_e32 v219, v219
	v_exp_f32_e32 v220, v220
	v_exp_f32_e32 v221, v221
	v_exp_f32_e32 v222, v222
	v_exp_f32_e32 v223, v223
	v_exp_f32_e32 v224, v224
	v_exp_f32_e32 v225, v225
	v_add_f32_e32 v218, 1.0, v218
	v_add_f32_e32 v219, 1.0, v219
	v_add_f32_e32 v220, 1.0, v220
	v_add_f32_e32 v221, 1.0, v221
	v_add_f32_e32 v222, 1.0, v222
	v_add_f32_e32 v223, 1.0, v223
	v_add_f32_e32 v224, 1.0, v224
	v_add_f32_e32 v225, 1.0, v225
	v_rcp_f32_e32 v218, v218
	v_rcp_f32_e32 v219, v219
	v_rcp_f32_e32 v220, v220
	v_rcp_f32_e32 v221, v221
	v_rcp_f32_e32 v222, v222
	v_rcp_f32_e32 v223, v223
	v_rcp_f32_e32 v224, v224
	v_rcp_f32_e32 v225, v225
	v_pk_mul_f32 v[102:103], v[102:103], v[218:219]
	v_pk_mul_f32 v[104:105], v[104:105], v[220:221]
	v_pk_mul_f32 v[98:99], v[98:99], v[222:223]
	v_pk_mul_f32 v[100:101], v[100:101], v[224:225]
	v_add_u32_e32 v217, 0x3e000, v216
	global_load_dwordx4 v[172:175], v217, s[94:95] offset:256
	s_waitcnt vmcnt(15)
	v_lshlrev_b32_e32 v218, 16, v176
	v_and_b32_e32 v219, 0xffff0000, v176
	v_lshlrev_b32_e32 v220, 16, v177
	v_and_b32_e32 v221, 0xffff0000, v177
	v_lshlrev_b32_e32 v222, 16, v178
	v_and_b32_e32 v223, 0xffff0000, v178
	v_lshlrev_b32_e32 v224, 16, v179
	v_and_b32_e32 v225, 0xffff0000, v179
	v_mul_f32_e32 v218, 0xbfb8aa3b, v218
	v_mul_f32_e32 v219, 0xbfb8aa3b, v219
	v_mul_f32_e32 v220, 0xbfb8aa3b, v220
	v_mul_f32_e32 v221, 0xbfb8aa3b, v221
	v_mul_f32_e32 v222, 0xbfb8aa3b, v222
	v_mul_f32_e32 v223, 0xbfb8aa3b, v223
	v_mul_f32_e32 v224, 0xbfb8aa3b, v224
	v_mul_f32_e32 v225, 0xbfb8aa3b, v225
	v_exp_f32_e32 v218, v218
	v_exp_f32_e32 v219, v219
	v_exp_f32_e32 v220, v220
	v_exp_f32_e32 v221, v221
	v_exp_f32_e32 v222, v222
	v_exp_f32_e32 v223, v223
	v_exp_f32_e32 v224, v224
	v_exp_f32_e32 v225, v225
	v_add_f32_e32 v218, 1.0, v218
	v_add_f32_e32 v219, 1.0, v219
	v_add_f32_e32 v220, 1.0, v220
	v_add_f32_e32 v221, 1.0, v221
	v_add_f32_e32 v222, 1.0, v222
	v_add_f32_e32 v223, 1.0, v223
	v_add_f32_e32 v224, 1.0, v224
	v_add_f32_e32 v225, 1.0, v225
	v_rcp_f32_e32 v218, v218
	v_rcp_f32_e32 v219, v219
	v_rcp_f32_e32 v220, v220
	v_rcp_f32_e32 v221, v221
	v_rcp_f32_e32 v222, v222
	v_rcp_f32_e32 v223, v223
	v_rcp_f32_e32 v224, v224
	v_rcp_f32_e32 v225, v225
	v_pk_mul_f32 v[94:95], v[94:95], v[218:219]
	v_pk_mul_f32 v[96:97], v[96:97], v[220:221]
	v_pk_mul_f32 v[90:91], v[90:91], v[222:223]
	v_pk_mul_f32 v[92:93], v[92:93], v[224:225]
	v_add_u32_e32 v217, 0x7c000, v216
	global_load_dwordx4 v[176:179], v217, s[94:95]
	s_waitcnt vmcnt(15)
	v_lshlrev_b32_e32 v218, 16, v180
	v_and_b32_e32 v219, 0xffff0000, v180
	v_lshlrev_b32_e32 v220, 16, v181
	v_and_b32_e32 v221, 0xffff0000, v181
	v_lshlrev_b32_e32 v222, 16, v182
	v_and_b32_e32 v223, 0xffff0000, v182
	v_lshlrev_b32_e32 v224, 16, v183
	v_and_b32_e32 v225, 0xffff0000, v183
	v_mul_f32_e32 v218, 0xbfb8aa3b, v218
	v_mul_f32_e32 v219, 0xbfb8aa3b, v219
	v_mul_f32_e32 v220, 0xbfb8aa3b, v220
	v_mul_f32_e32 v221, 0xbfb8aa3b, v221
	v_mul_f32_e32 v222, 0xbfb8aa3b, v222
	v_mul_f32_e32 v223, 0xbfb8aa3b, v223
	v_mul_f32_e32 v224, 0xbfb8aa3b, v224
	v_mul_f32_e32 v225, 0xbfb8aa3b, v225
	v_exp_f32_e32 v218, v218
	v_exp_f32_e32 v219, v219
	v_exp_f32_e32 v220, v220
	v_exp_f32_e32 v221, v221
	v_exp_f32_e32 v222, v222
	v_exp_f32_e32 v223, v223
	v_exp_f32_e32 v224, v224
	v_exp_f32_e32 v225, v225
	v_add_f32_e32 v218, 1.0, v218
	v_add_f32_e32 v219, 1.0, v219
	v_add_f32_e32 v220, 1.0, v220
	v_add_f32_e32 v221, 1.0, v221
	v_add_f32_e32 v222, 1.0, v222
	v_add_f32_e32 v223, 1.0, v223
	v_add_f32_e32 v224, 1.0, v224
	v_add_f32_e32 v225, 1.0, v225
	v_rcp_f32_e32 v218, v218
	v_rcp_f32_e32 v219, v219
	v_rcp_f32_e32 v220, v220
	v_rcp_f32_e32 v221, v221
	v_rcp_f32_e32 v222, v222
	v_rcp_f32_e32 v223, v223
	v_rcp_f32_e32 v224, v224
	v_rcp_f32_e32 v225, v225
	v_pk_mul_f32 v[86:87], v[86:87], v[218:219]
	v_pk_mul_f32 v[88:89], v[88:89], v[220:221]
	v_pk_mul_f32 v[82:83], v[82:83], v[222:223]
	v_pk_mul_f32 v[84:85], v[84:85], v[224:225]
	v_add_u32_e32 v217, 0x7c000, v216
	global_load_dwordx4 v[180:183], v217, s[94:95] offset:256
	s_waitcnt vmcnt(15)
	v_lshlrev_b32_e32 v218, 16, v184
	v_and_b32_e32 v219, 0xffff0000, v184
	v_lshlrev_b32_e32 v220, 16, v185
	v_and_b32_e32 v221, 0xffff0000, v185
	v_lshlrev_b32_e32 v222, 16, v186
	v_and_b32_e32 v223, 0xffff0000, v186
	v_lshlrev_b32_e32 v224, 16, v187
	v_and_b32_e32 v225, 0xffff0000, v187
	v_mul_f32_e32 v218, 0xbfb8aa3b, v218
	v_mul_f32_e32 v219, 0xbfb8aa3b, v219
	v_mul_f32_e32 v220, 0xbfb8aa3b, v220
	v_mul_f32_e32 v221, 0xbfb8aa3b, v221
	v_mul_f32_e32 v222, 0xbfb8aa3b, v222
	v_mul_f32_e32 v223, 0xbfb8aa3b, v223
	v_mul_f32_e32 v224, 0xbfb8aa3b, v224
	v_mul_f32_e32 v225, 0xbfb8aa3b, v225
	v_exp_f32_e32 v218, v218
	v_exp_f32_e32 v219, v219
	v_exp_f32_e32 v220, v220
	v_exp_f32_e32 v221, v221
	v_exp_f32_e32 v222, v222
	v_exp_f32_e32 v223, v223
	v_exp_f32_e32 v224, v224
	v_exp_f32_e32 v225, v225
	v_add_f32_e32 v218, 1.0, v218
	v_add_f32_e32 v219, 1.0, v219
	v_add_f32_e32 v220, 1.0, v220
	v_add_f32_e32 v221, 1.0, v221
	v_add_f32_e32 v222, 1.0, v222
	v_add_f32_e32 v223, 1.0, v223
	v_add_f32_e32 v224, 1.0, v224
	v_add_f32_e32 v225, 1.0, v225
	v_rcp_f32_e32 v218, v218
	v_rcp_f32_e32 v219, v219
	v_rcp_f32_e32 v220, v220
	v_rcp_f32_e32 v221, v221
	v_rcp_f32_e32 v222, v222
	v_rcp_f32_e32 v223, v223
	v_rcp_f32_e32 v224, v224
	v_rcp_f32_e32 v225, v225
	v_pk_mul_f32 v[78:79], v[78:79], v[218:219]
	v_pk_mul_f32 v[80:81], v[80:81], v[220:221]
	v_pk_mul_f32 v[74:75], v[74:75], v[222:223]
	v_pk_mul_f32 v[76:77], v[76:77], v[224:225]
	v_add_u32_e32 v217, 0xba000, v216
	global_load_dwordx4 v[184:187], v217, s[94:95]
	s_waitcnt vmcnt(15)
; __device__ __forceinline__ float sigm(float x) { return __builtin_amdgcn_rcpf(1.f + fexp(-x)); }
;     __device__ __forceinline__ void operator()(const f32x4 (&acc)[2][2][4][2], const Unit& u, int wr, int wc, int fr, int fq) const {
;     ...
;                         const u32x4 b = *(const u32x4*)(rowp + C_MB + bj * HALF);
;                         float mb[8] = {bflo(b.x), bfhi(b.x), bflo(b.y), bfhi(b.y), bflo(b.z), bfhi(b.z), bflo(b.w), bfhi(b.w)};
; #pragma unroll
;                         for (int e = 0; e < 8; ++e) o[e] = ma[e] + acc[ai][bj][m][e >> 2][e & 3] * sigm(mb[e]);
	v_lshlrev_b32_e32 v218, 16, v188
	v_and_b32_e32 v219, 0xffff0000, v188
	v_lshlrev_b32_e32 v220, 16, v189
	v_and_b32_e32 v221, 0xffff0000, v189
	v_lshlrev_b32_e32 v222, 16, v190
	v_and_b32_e32 v223, 0xffff0000, v190
	v_lshlrev_b32_e32 v224, 16, v191
	v_and_b32_e32 v225, 0xffff0000, v191
	v_mul_f32_e32 v218, 0xbfb8aa3b, v218
	v_mul_f32_e32 v219, 0xbfb8aa3b, v219
	v_mul_f32_e32 v220, 0xbfb8aa3b, v220
	v_mul_f32_e32 v221, 0xbfb8aa3b, v221
	v_mul_f32_e32 v222, 0xbfb8aa3b, v222
	v_mul_f32_e32 v223, 0xbfb8aa3b, v223
	v_mul_f32_e32 v224, 0xbfb8aa3b, v224
	v_mul_f32_e32 v225, 0xbfb8aa3b, v225
	v_exp_f32_e32 v218, v218
	v_exp_f32_e32 v219, v219
	v_exp_f32_e32 v220, v220
	v_exp_f32_e32 v221, v221
	v_exp_f32_e32 v222, v222
	v_exp_f32_e32 v223, v223
	v_exp_f32_e32 v224, v224
	v_exp_f32_e32 v225, v225
	v_add_f32_e32 v218, 1.0, v218
	v_add_f32_e32 v219, 1.0, v219
	v_add_f32_e32 v220, 1.0, v220
	v_add_f32_e32 v221, 1.0, v221
	v_add_f32_e32 v222, 1.0, v222
	v_add_f32_e32 v223, 1.0, v223
	v_add_f32_e32 v224, 1.0, v224
	v_add_f32_e32 v225, 1.0, v225
	v_rcp_f32_e32 v218, v218
	v_rcp_f32_e32 v219, v219
	v_rcp_f32_e32 v220, v220
	v_rcp_f32_e32 v221, v221
	v_rcp_f32_e32 v222, v222
	v_rcp_f32_e32 v223, v223
	v_rcp_f32_e32 v224, v224
	v_rcp_f32_e32 v225, v225
	v_pk_mul_f32 v[70:71], v[70:71], v[218:219]
	v_pk_mul_f32 v[72:73], v[72:73], v[220:221]
	v_pk_mul_f32 v[66:67], v[66:67], v[222:223]
	v_pk_mul_f32 v[68:69], v[68:69], v[224:225]
	v_add_u32_e32 v217, 0xba000, v216
	global_load_dwordx4 v[188:191], v217, s[94:95] offset:256
	s_waitcnt vmcnt(15)
	v_lshlrev_b32_e32 v218, 16, v192
	v_and_b32_e32 v219, 0xffff0000, v192
	v_lshlrev_b32_e32 v220, 16, v193
	v_and_b32_e32 v221, 0xffff0000, v193
	v_lshlrev_b32_e32 v222, 16, v194
	v_and_b32_e32 v223, 0xffff0000, v194
	v_lshlrev_b32_e32 v224, 16, v195
	v_and_b32_e32 v225, 0xffff0000, v195
	v_mul_f32_e32 v218, 0xbfb8aa3b, v218
	v_mul_f32_e32 v219, 0xbfb8aa3b, v219
	v_mul_f32_e32 v220, 0xbfb8aa3b, v220
	v_mul_f32_e32 v221, 0xbfb8aa3b, v221
	v_mul_f32_e32 v222, 0xbfb8aa3b, v222
	v_mul_f32_e32 v223, 0xbfb8aa3b, v223
	v_mul_f32_e32 v224, 0xbfb8aa3b, v224
	v_mul_f32_e32 v225, 0xbfb8aa3b, v225
	v_exp_f32_e32 v218, v218
	v_exp_f32_e32 v219, v219
	v_exp_f32_e32 v220, v220
	v_exp_f32_e32 v221, v221
	v_exp_f32_e32 v222, v222
	v_exp_f32_e32 v223, v223
	v_exp_f32_e32 v224, v224
	v_exp_f32_e32 v225, v225
	v_add_f32_e32 v218, 1.0, v218
	v_add_f32_e32 v219, 1.0, v219
	v_add_f32_e32 v220, 1.0, v220
	v_add_f32_e32 v221, 1.0, v221
	v_add_f32_e32 v222, 1.0, v222
	v_add_f32_e32 v223, 1.0, v223
	v_add_f32_e32 v224, 1.0, v224
	v_add_f32_e32 v225, 1.0, v225
	v_rcp_f32_e32 v218, v218
	v_rcp_f32_e32 v219, v219
	v_rcp_f32_e32 v220, v220
	v_rcp_f32_e32 v221, v221
	v_rcp_f32_e32 v222, v222
	v_rcp_f32_e32 v223, v223
	v_rcp_f32_e32 v224, v224
	v_rcp_f32_e32 v225, v225
	v_pk_mul_f32 v[62:63], v[62:63], v[218:219]
	v_pk_mul_f32 v[64:65], v[64:65], v[220:221]
	v_pk_mul_f32 v[58:59], v[58:59], v[222:223]
	v_pk_mul_f32 v[60:61], v[60:61], v[224:225]
	v_add_u32_e32 v217, 0x1f0000, v216
	global_load_dwordx4 v[192:195], v217, s[94:95]
	s_waitcnt vmcnt(15)
	v_lshlrev_b32_e32 v218, 16, v196
	v_and_b32_e32 v219, 0xffff0000, v196
	v_lshlrev_b32_e32 v220, 16, v197
	v_and_b32_e32 v221, 0xffff0000, v197
	v_lshlrev_b32_e32 v222, 16, v198
	v_and_b32_e32 v223, 0xffff0000, v198
	v_lshlrev_b32_e32 v224, 16, v199
	v_and_b32_e32 v225, 0xffff0000, v199
	v_mul_f32_e32 v218, 0xbfb8aa3b, v218
	v_mul_f32_e32 v219, 0xbfb8aa3b, v219
	v_mul_f32_e32 v220, 0xbfb8aa3b, v220
	v_mul_f32_e32 v221, 0xbfb8aa3b, v221
	v_mul_f32_e32 v222, 0xbfb8aa3b, v222
	v_mul_f32_e32 v223, 0xbfb8aa3b, v223
	v_mul_f32_e32 v224, 0xbfb8aa3b, v224
	v_mul_f32_e32 v225, 0xbfb8aa3b, v225
	v_exp_f32_e32 v218, v218
	v_exp_f32_e32 v219, v219
	v_exp_f32_e32 v220, v220
	v_exp_f32_e32 v221, v221
	v_exp_f32_e32 v222, v222
	v_exp_f32_e32 v223, v223
	v_exp_f32_e32 v224, v224
	v_exp_f32_e32 v225, v225
	v_add_f32_e32 v218, 1.0, v218
	v_add_f32_e32 v219, 1.0, v219
	v_add_f32_e32 v220, 1.0, v220
	v_add_f32_e32 v221, 1.0, v221
	v_add_f32_e32 v222, 1.0, v222
	v_add_f32_e32 v223, 1.0, v223
	v_add_f32_e32 v224, 1.0, v224
	v_add_f32_e32 v225, 1.0, v225
	v_rcp_f32_e32 v218, v218
	v_rcp_f32_e32 v219, v219
	v_rcp_f32_e32 v220, v220
	v_rcp_f32_e32 v221, v221
	v_rcp_f32_e32 v222, v222
	v_rcp_f32_e32 v223, v223
	v_rcp_f32_e32 v224, v224
	v_rcp_f32_e32 v225, v225
	v_pk_mul_f32 v[54:55], v[54:55], v[218:219]
	v_pk_mul_f32 v[56:57], v[56:57], v[220:221]
	v_pk_mul_f32 v[50:51], v[50:51], v[222:223]
	v_pk_mul_f32 v[52:53], v[52:53], v[224:225]
	v_add_u32_e32 v217, 0x1f0000, v216
	global_load_dwordx4 v[196:199], v217, s[94:95] offset:256
	s_waitcnt vmcnt(15)
	v_lshlrev_b32_e32 v218, 16, v200
	v_and_b32_e32 v219, 0xffff0000, v200
	v_lshlrev_b32_e32 v220, 16, v201
	v_and_b32_e32 v221, 0xffff0000, v201
	v_lshlrev_b32_e32 v222, 16, v202
	v_and_b32_e32 v223, 0xffff0000, v202
	v_lshlrev_b32_e32 v224, 16, v203
	v_and_b32_e32 v225, 0xffff0000, v203
	v_mul_f32_e32 v218, 0xbfb8aa3b, v218
	v_mul_f32_e32 v219, 0xbfb8aa3b, v219
	v_mul_f32_e32 v220, 0xbfb8aa3b, v220
	v_mul_f32_e32 v221, 0xbfb8aa3b, v221
	v_mul_f32_e32 v222, 0xbfb8aa3b, v222
	v_mul_f32_e32 v223, 0xbfb8aa3b, v223
	v_mul_f32_e32 v224, 0xbfb8aa3b, v224
	v_mul_f32_e32 v225, 0xbfb8aa3b, v225
	v_exp_f32_e32 v218, v218
	v_exp_f32_e32 v219, v219
	v_exp_f32_e32 v220, v220
	v_exp_f32_e32 v221, v221
	v_exp_f32_e32 v222, v222
	v_exp_f32_e32 v223, v223
	v_exp_f32_e32 v224, v224
	v_exp_f32_e32 v225, v225
	v_add_f32_e32 v218, 1.0, v218
	v_add_f32_e32 v219, 1.0, v219
	v_add_f32_e32 v220, 1.0, v220
	v_add_f32_e32 v221, 1.0, v221
	v_add_f32_e32 v222, 1.0, v222
	v_add_f32_e32 v223, 1.0, v223
	v_add_f32_e32 v224, 1.0, v224
	v_add_f32_e32 v225, 1.0, v225
	v_rcp_f32_e32 v218, v218
	v_rcp_f32_e32 v219, v219
	v_rcp_f32_e32 v220, v220
	v_rcp_f32_e32 v221, v221
	v_rcp_f32_e32 v222, v222
	v_rcp_f32_e32 v223, v223
	v_rcp_f32_e32 v224, v224
	v_rcp_f32_e32 v225, v225
	v_pk_mul_f32 v[46:47], v[46:47], v[218:219]
	v_pk_mul_f32 v[48:49], v[48:49], v[220:221]
	v_pk_mul_f32 v[42:43], v[42:43], v[222:223]
	v_pk_mul_f32 v[44:45], v[44:45], v[224:225]
	v_add_u32_e32 v217, 0x22e000, v216
	global_load_dwordx4 v[200:203], v217, s[94:95]
	s_waitcnt vmcnt(15)
; __device__ __forceinline__ float sigm(float x) { return __builtin_amdgcn_rcpf(1.f + fexp(-x)); }
;     __device__ __forceinline__ void operator()(const f32x4 (&acc)[2][2][4][2], const Unit& u, int wr, int wc, int fr, int fq) const {
;     ...
;                         const u32x4 b = *(const u32x4*)(rowp + C_MB + bj * HALF);
;                         float mb[8] = {bflo(b.x), bfhi(b.x), bflo(b.y), bfhi(b.y), bflo(b.z), bfhi(b.z), bflo(b.w), bfhi(b.w)};
; #pragma unroll
;                         for (int e = 0; e < 8; ++e) o[e] = ma[e] + acc[ai][bj][m][e >> 2][e & 3] * sigm(mb[e]);
	v_lshlrev_b32_e32 v218, 16, v204
	v_and_b32_e32 v219, 0xffff0000, v204
	v_lshlrev_b32_e32 v220, 16, v205
	v_and_b32_e32 v221, 0xffff0000, v205
	v_lshlrev_b32_e32 v222, 16, v206
	v_and_b32_e32 v223, 0xffff0000, v206
	v_lshlrev_b32_e32 v224, 16, v207
	v_and_b32_e32 v225, 0xffff0000, v207
	v_mul_f32_e32 v218, 0xbfb8aa3b, v218
	v_mul_f32_e32 v219, 0xbfb8aa3b, v219
	v_mul_f32_e32 v220, 0xbfb8aa3b, v220
	v_mul_f32_e32 v221, 0xbfb8aa3b, v221
	v_mul_f32_e32 v222, 0xbfb8aa3b, v222
	v_mul_f32_e32 v223, 0xbfb8aa3b, v223
	v_mul_f32_e32 v224, 0xbfb8aa3b, v224
	v_mul_f32_e32 v225, 0xbfb8aa3b, v225
	v_exp_f32_e32 v218, v218
	v_exp_f32_e32 v219, v219
	v_exp_f32_e32 v220, v220
	v_exp_f32_e32 v221, v221
	v_exp_f32_e32 v222, v222
	v_exp_f32_e32 v223, v223
	v_exp_f32_e32 v224, v224
	v_exp_f32_e32 v225, v225
	v_add_f32_e32 v218, 1.0, v218
	v_add_f32_e32 v219, 1.0, v219
	v_add_f32_e32 v220, 1.0, v220
	v_add_f32_e32 v221, 1.0, v221
	v_add_f32_e32 v222, 1.0, v222
	v_add_f32_e32 v223, 1.0, v223
	v_add_f32_e32 v224, 1.0, v224
	v_add_f32_e32 v225, 1.0, v225
	v_rcp_f32_e32 v218, v218
	v_rcp_f32_e32 v219, v219
	v_rcp_f32_e32 v220, v220
	v_rcp_f32_e32 v221, v221
	v_rcp_f32_e32 v222, v222
	v_rcp_f32_e32 v223, v223
	v_rcp_f32_e32 v224, v224
	v_rcp_f32_e32 v225, v225
	v_pk_mul_f32 v[38:39], v[38:39], v[218:219]
	v_pk_mul_f32 v[40:41], v[40:41], v[220:221]
	v_pk_mul_f32 v[34:35], v[34:35], v[222:223]
	v_pk_mul_f32 v[36:37], v[36:37], v[224:225]
	v_add_u32_e32 v217, 0x22e000, v216
	global_load_dwordx4 v[204:207], v217, s[94:95] offset:256
	s_waitcnt vmcnt(15)
	v_lshlrev_b32_e32 v218, 16, v130
	v_and_b32_e32 v219, 0xffff0000, v130
	v_lshlrev_b32_e32 v220, 16, v131
	v_and_b32_e32 v221, 0xffff0000, v131
	v_lshlrev_b32_e32 v222, 16, v132
	v_and_b32_e32 v223, 0xffff0000, v132
	v_lshlrev_b32_e32 v224, 16, v133
	v_and_b32_e32 v225, 0xffff0000, v133
	v_mul_f32_e32 v218, 0xbfb8aa3b, v218
	v_mul_f32_e32 v219, 0xbfb8aa3b, v219
	v_mul_f32_e32 v220, 0xbfb8aa3b, v220
	v_mul_f32_e32 v221, 0xbfb8aa3b, v221
	v_mul_f32_e32 v222, 0xbfb8aa3b, v222
	v_mul_f32_e32 v223, 0xbfb8aa3b, v223
	v_mul_f32_e32 v224, 0xbfb8aa3b, v224
	v_mul_f32_e32 v225, 0xbfb8aa3b, v225
	v_exp_f32_e32 v218, v218
	v_exp_f32_e32 v219, v219
	v_exp_f32_e32 v220, v220
	v_exp_f32_e32 v221, v221
	v_exp_f32_e32 v222, v222
	v_exp_f32_e32 v223, v223
	v_exp_f32_e32 v224, v224
	v_exp_f32_e32 v225, v225
	v_add_f32_e32 v218, 1.0, v218
	v_add_f32_e32 v219, 1.0, v219
	v_add_f32_e32 v220, 1.0, v220
	v_add_f32_e32 v221, 1.0, v221
	v_add_f32_e32 v222, 1.0, v222
	v_add_f32_e32 v223, 1.0, v223
	v_add_f32_e32 v224, 1.0, v224
	v_add_f32_e32 v225, 1.0, v225
	v_rcp_f32_e32 v218, v218
	v_rcp_f32_e32 v219, v219
	v_rcp_f32_e32 v220, v220
	v_rcp_f32_e32 v221, v221
	v_rcp_f32_e32 v222, v222
	v_rcp_f32_e32 v223, v223
	v_rcp_f32_e32 v224, v224
	v_rcp_f32_e32 v225, v225
	v_pk_mul_f32 v[30:31], v[30:31], v[218:219]
	v_pk_mul_f32 v[32:33], v[32:33], v[220:221]
	v_pk_mul_f32 v[26:27], v[26:27], v[222:223]
	v_pk_mul_f32 v[28:29], v[28:29], v[224:225]
	v_add_u32_e32 v217, 0x26c000, v216
	global_load_dwordx4 v[130:133], v217, s[94:95]
	s_waitcnt vmcnt(15)
	v_lshlrev_b32_e32 v218, 16, v134
	v_and_b32_e32 v219, 0xffff0000, v134
	v_lshlrev_b32_e32 v220, 16, v135
	v_and_b32_e32 v221, 0xffff0000, v135
	v_lshlrev_b32_e32 v222, 16, v136
	v_and_b32_e32 v223, 0xffff0000, v136
	v_lshlrev_b32_e32 v224, 16, v137
	v_and_b32_e32 v225, 0xffff0000, v137
	v_mul_f32_e32 v218, 0xbfb8aa3b, v218
	v_mul_f32_e32 v219, 0xbfb8aa3b, v219
	v_mul_f32_e32 v220, 0xbfb8aa3b, v220
	v_mul_f32_e32 v221, 0xbfb8aa3b, v221
	v_mul_f32_e32 v222, 0xbfb8aa3b, v222
	v_mul_f32_e32 v223, 0xbfb8aa3b, v223
	v_mul_f32_e32 v224, 0xbfb8aa3b, v224
	v_mul_f32_e32 v225, 0xbfb8aa3b, v225
	v_exp_f32_e32 v218, v218
	v_exp_f32_e32 v219, v219
	v_exp_f32_e32 v220, v220
	v_exp_f32_e32 v221, v221
	v_exp_f32_e32 v222, v222
	v_exp_f32_e32 v223, v223
	v_exp_f32_e32 v224, v224
	v_exp_f32_e32 v225, v225
	v_add_f32_e32 v218, 1.0, v218
	v_add_f32_e32 v219, 1.0, v219
	v_add_f32_e32 v220, 1.0, v220
	v_add_f32_e32 v221, 1.0, v221
	v_add_f32_e32 v222, 1.0, v222
	v_add_f32_e32 v223, 1.0, v223
	v_add_f32_e32 v224, 1.0, v224
	v_add_f32_e32 v225, 1.0, v225
	v_rcp_f32_e32 v218, v218
	v_rcp_f32_e32 v219, v219
	v_rcp_f32_e32 v220, v220
	v_rcp_f32_e32 v221, v221
	v_rcp_f32_e32 v222, v222
	v_rcp_f32_e32 v223, v223
	v_rcp_f32_e32 v224, v224
	v_rcp_f32_e32 v225, v225
	v_pk_mul_f32 v[22:23], v[22:23], v[218:219]
	v_pk_mul_f32 v[24:25], v[24:25], v[220:221]
	v_pk_mul_f32 v[18:19], v[18:19], v[222:223]
	v_pk_mul_f32 v[20:21], v[20:21], v[224:225]
	v_add_u32_e32 v217, 0x26c000, v216
	global_load_dwordx4 v[134:137], v217, s[94:95] offset:256
	s_waitcnt vmcnt(15)
	v_lshlrev_b32_e32 v218, 16, v148
	v_and_b32_e32 v219, 0xffff0000, v148
	v_lshlrev_b32_e32 v220, 16, v149
	v_and_b32_e32 v221, 0xffff0000, v149
	v_lshlrev_b32_e32 v222, 16, v150
	v_and_b32_e32 v223, 0xffff0000, v150
	v_lshlrev_b32_e32 v224, 16, v151
	v_and_b32_e32 v225, 0xffff0000, v151
	v_mul_f32_e32 v218, 0xbfb8aa3b, v218
	v_mul_f32_e32 v219, 0xbfb8aa3b, v219
	v_mul_f32_e32 v220, 0xbfb8aa3b, v220
	v_mul_f32_e32 v221, 0xbfb8aa3b, v221
	v_mul_f32_e32 v222, 0xbfb8aa3b, v222
	v_mul_f32_e32 v223, 0xbfb8aa3b, v223
	v_mul_f32_e32 v224, 0xbfb8aa3b, v224
	v_mul_f32_e32 v225, 0xbfb8aa3b, v225
	v_exp_f32_e32 v218, v218
	v_exp_f32_e32 v219, v219
	v_exp_f32_e32 v220, v220
	v_exp_f32_e32 v221, v221
	v_exp_f32_e32 v222, v222
	v_exp_f32_e32 v223, v223
	v_exp_f32_e32 v224, v224
	v_exp_f32_e32 v225, v225
	v_add_f32_e32 v218, 1.0, v218
	v_add_f32_e32 v219, 1.0, v219
	v_add_f32_e32 v220, 1.0, v220
	v_add_f32_e32 v221, 1.0, v221
	v_add_f32_e32 v222, 1.0, v222
	v_add_f32_e32 v223, 1.0, v223
	v_add_f32_e32 v224, 1.0, v224
	v_add_f32_e32 v225, 1.0, v225
	v_rcp_f32_e32 v218, v218
	v_rcp_f32_e32 v219, v219
	v_rcp_f32_e32 v220, v220
	v_rcp_f32_e32 v221, v221
	v_rcp_f32_e32 v222, v222
	v_rcp_f32_e32 v223, v223
	v_rcp_f32_e32 v224, v224
	v_rcp_f32_e32 v225, v225
	v_pk_mul_f32 v[14:15], v[14:15], v[218:219]
	v_pk_mul_f32 v[16:17], v[16:17], v[220:221]
	v_pk_mul_f32 v[10:11], v[10:11], v[222:223]
	v_pk_mul_f32 v[12:13], v[12:13], v[224:225]
	v_add_u32_e32 v217, 0x2aa000, v216
	global_load_dwordx4 v[148:151], v217, s[94:95]
	s_waitcnt vmcnt(15)
; __device__ __forceinline__ unsigned pk2(float lo, float hi) { f32x2 v = {lo, hi}; bf16x2_t b = __builtin_convertvector(v, bf16x2_t); return __builtin_bit_cast(unsigned, b); }
; __device__ __forceinline__ float sigm(float x) { return __builtin_amdgcn_rcpf(1.f + fexp(-x)); }
;     __device__ __forceinline__ void operator()(const f32x4 (&acc)[2][2][4][2], const Unit& u, int wr, int wc, int fr, int fq) const {
;     ...
;                         const u32x4 b = *(const u32x4*)(rowp + C_MB + bj * HALF);
;                         float mb[8] = {bflo(b.x), bfhi(b.x), bflo(b.y), bfhi(b.y), bflo(b.z), bfhi(b.z), bflo(b.w), bfhi(b.w)};
; #pragma unroll
;                         for (int e = 0; e < 8; ++e) o[e] = ma[e] + acc[ai][bj][m][e >> 2][e & 3] * sigm(mb[e]);
;                     } else {
; #pragma unroll
;                         for (int e = 0; e < 8; ++e) o[e] = acc[ai][bj][m][e >> 2][e & 3] * sigm(ma[e]);
;                     }
;                     u32x4 w; w.x = pk2(o[0], o[1]); w.y = pk2(o[2], o[3]); w.z = pk2(o[4], o[5]); w.w = pk2(o[6], o[7]);
;                     *(u32x4*)(roww + C_MA + bj * HALF) = w;
	v_lshlrev_b32_e32 v218, 16, v152
	v_and_b32_e32 v219, 0xffff0000, v152
	v_lshlrev_b32_e32 v220, 16, v153
	v_and_b32_e32 v221, 0xffff0000, v153
	v_lshlrev_b32_e32 v222, 16, v154
	v_and_b32_e32 v223, 0xffff0000, v154
	v_lshlrev_b32_e32 v224, 16, v155
	v_and_b32_e32 v225, 0xffff0000, v155
	v_mul_f32_e32 v218, 0xbfb8aa3b, v218
	v_mul_f32_e32 v219, 0xbfb8aa3b, v219
	v_mul_f32_e32 v220, 0xbfb8aa3b, v220
	v_mul_f32_e32 v221, 0xbfb8aa3b, v221
	v_mul_f32_e32 v222, 0xbfb8aa3b, v222
	v_mul_f32_e32 v223, 0xbfb8aa3b, v223
	v_mul_f32_e32 v224, 0xbfb8aa3b, v224
	v_mul_f32_e32 v225, 0xbfb8aa3b, v225
	v_exp_f32_e32 v218, v218
	v_exp_f32_e32 v219, v219
	v_exp_f32_e32 v220, v220
	v_exp_f32_e32 v221, v221
	v_exp_f32_e32 v222, v222
	v_exp_f32_e32 v223, v223
	v_exp_f32_e32 v224, v224
	v_exp_f32_e32 v225, v225
	v_add_f32_e32 v218, 1.0, v218
	v_add_f32_e32 v219, 1.0, v219
	v_add_f32_e32 v220, 1.0, v220
	v_add_f32_e32 v221, 1.0, v221
	v_add_f32_e32 v222, 1.0, v222
	v_add_f32_e32 v223, 1.0, v223
	v_add_f32_e32 v224, 1.0, v224
	v_add_f32_e32 v225, 1.0, v225
	v_rcp_f32_e32 v218, v218
	v_rcp_f32_e32 v219, v219
	v_rcp_f32_e32 v220, v220
	v_rcp_f32_e32 v221, v221
	v_rcp_f32_e32 v222, v222
	v_rcp_f32_e32 v223, v223
	v_rcp_f32_e32 v224, v224
	v_rcp_f32_e32 v225, v225
	v_pk_mul_f32 v[6:7], v[6:7], v[218:219]
	v_pk_mul_f32 v[8:9], v[8:9], v[220:221]
	v_pk_mul_f32 v[2:3], v[2:3], v[222:223]
	v_pk_mul_f32 v[4:5], v[4:5], v[224:225]
	v_add_u32_e32 v217, 0x2aa000, v216
	global_load_dwordx4 v[152:155], v217, s[94:95] offset:256
	s_waitcnt vmcnt(15)
	v_lshlrev_b32_e32 v218, 16, v160
	v_and_b32_e32 v219, 0xffff0000, v160
	v_lshlrev_b32_e32 v220, 16, v161
	v_and_b32_e32 v221, 0xffff0000, v161
	v_lshlrev_b32_e32 v222, 16, v162
	v_and_b32_e32 v223, 0xffff0000, v162
	v_lshlrev_b32_e32 v224, 16, v163
	v_and_b32_e32 v225, 0xffff0000, v163
	v_pk_add_f32 v[126:127], v[126:127], v[218:219]
	v_pk_add_f32 v[128:129], v[128:129], v[220:221]
	v_pk_add_f32 v[122:123], v[122:123], v[222:223]
	v_pk_add_f32 v[124:125], v[124:125], v[224:225]
	v_cvt_pk_bf16_f32 v160, v126, v127
	v_cvt_pk_bf16_f32 v161, v128, v129
	v_cvt_pk_bf16_f32 v162, v122, v123
	v_cvt_pk_bf16_f32 v163, v124, v125
	global_store_dwordx4 v216, v[160:163], s[94:95]
	s_waitcnt vmcnt(15)
	v_lshlrev_b32_e32 v218, 16, v164
	v_and_b32_e32 v219, 0xffff0000, v164
	v_lshlrev_b32_e32 v220, 16, v165
	v_and_b32_e32 v221, 0xffff0000, v165
	v_lshlrev_b32_e32 v222, 16, v166
	v_and_b32_e32 v223, 0xffff0000, v166
	v_lshlrev_b32_e32 v224, 16, v167
	v_and_b32_e32 v225, 0xffff0000, v167
	v_pk_add_f32 v[118:119], v[118:119], v[218:219]
	v_pk_add_f32 v[120:121], v[120:121], v[220:221]
	v_pk_add_f32 v[114:115], v[114:115], v[222:223]
	v_pk_add_f32 v[116:117], v[116:117], v[224:225]
	v_cvt_pk_bf16_f32 v164, v118, v119
	v_cvt_pk_bf16_f32 v165, v120, v121
	v_cvt_pk_bf16_f32 v166, v114, v115
	v_cvt_pk_bf16_f32 v167, v116, v117
	global_store_dwordx4 v216, v[164:167], s[94:95] offset:256
	s_waitcnt vmcnt(15)
	v_lshlrev_b32_e32 v218, 16, v168
	v_and_b32_e32 v219, 0xffff0000, v168
	v_lshlrev_b32_e32 v220, 16, v169
	v_and_b32_e32 v221, 0xffff0000, v169
	v_lshlrev_b32_e32 v222, 16, v170
	v_and_b32_e32 v223, 0xffff0000, v170
	v_lshlrev_b32_e32 v224, 16, v171
	v_and_b32_e32 v225, 0xffff0000, v171
	v_pk_add_f32 v[110:111], v[110:111], v[218:219]
	v_pk_add_f32 v[112:113], v[112:113], v[220:221]
	v_pk_add_f32 v[106:107], v[106:107], v[222:223]
	v_pk_add_f32 v[108:109], v[108:109], v[224:225]
	v_cvt_pk_bf16_f32 v168, v110, v111
	v_cvt_pk_bf16_f32 v169, v112, v113
	v_cvt_pk_bf16_f32 v170, v106, v107
	v_cvt_pk_bf16_f32 v171, v108, v109
	v_add_u32_e32 v217, 0x3e000, v216
	global_store_dwordx4 v217, v[168:171], s[94:95]
	s_waitcnt vmcnt(15)
	v_lshlrev_b32_e32 v218, 16, v172
	v_and_b32_e32 v219, 0xffff0000, v172
	v_lshlrev_b32_e32 v220, 16, v173
	v_and_b32_e32 v221, 0xffff0000, v173
	v_lshlrev_b32_e32 v222, 16, v174
	v_and_b32_e32 v223, 0xffff0000, v174
	v_lshlrev_b32_e32 v224, 16, v175
	v_and_b32_e32 v225, 0xffff0000, v175
	v_pk_add_f32 v[102:103], v[102:103], v[218:219]
	v_pk_add_f32 v[104:105], v[104:105], v[220:221]
	v_pk_add_f32 v[98:99], v[98:99], v[222:223]
	v_pk_add_f32 v[100:101], v[100:101], v[224:225]
	v_cvt_pk_bf16_f32 v172, v102, v103
	v_cvt_pk_bf16_f32 v173, v104, v105
	v_cvt_pk_bf16_f32 v174, v98, v99
	v_cvt_pk_bf16_f32 v175, v100, v101
	v_add_u32_e32 v217, 0x3e000, v216
	global_store_dwordx4 v217, v[172:175], s[94:95] offset:256
	s_waitcnt vmcnt(15)
	v_lshlrev_b32_e32 v218, 16, v176
	v_and_b32_e32 v219, 0xffff0000, v176
	v_lshlrev_b32_e32 v220, 16, v177
	v_and_b32_e32 v221, 0xffff0000, v177
	v_lshlrev_b32_e32 v222, 16, v178
	v_and_b32_e32 v223, 0xffff0000, v178
	v_lshlrev_b32_e32 v224, 16, v179
	v_and_b32_e32 v225, 0xffff0000, v179
	v_pk_add_f32 v[94:95], v[94:95], v[218:219]
	v_pk_add_f32 v[96:97], v[96:97], v[220:221]
	v_pk_add_f32 v[90:91], v[90:91], v[222:223]
	v_pk_add_f32 v[92:93], v[92:93], v[224:225]
	v_cvt_pk_bf16_f32 v176, v94, v95
	v_cvt_pk_bf16_f32 v177, v96, v97
	v_cvt_pk_bf16_f32 v178, v90, v91
	v_cvt_pk_bf16_f32 v179, v92, v93
	v_add_u32_e32 v217, 0x7c000, v216
	global_store_dwordx4 v217, v[176:179], s[94:95]
	s_waitcnt vmcnt(15)
	v_lshlrev_b32_e32 v218, 16, v180
	v_and_b32_e32 v219, 0xffff0000, v180
	v_lshlrev_b32_e32 v220, 16, v181
	v_and_b32_e32 v221, 0xffff0000, v181
	v_lshlrev_b32_e32 v222, 16, v182
	v_and_b32_e32 v223, 0xffff0000, v182
	v_lshlrev_b32_e32 v224, 16, v183
	v_and_b32_e32 v225, 0xffff0000, v183
	v_pk_add_f32 v[86:87], v[86:87], v[218:219]
	v_pk_add_f32 v[88:89], v[88:89], v[220:221]
	v_pk_add_f32 v[82:83], v[82:83], v[222:223]
	v_pk_add_f32 v[84:85], v[84:85], v[224:225]
	v_cvt_pk_bf16_f32 v180, v86, v87
	v_cvt_pk_bf16_f32 v181, v88, v89
	v_cvt_pk_bf16_f32 v182, v82, v83
	v_cvt_pk_bf16_f32 v183, v84, v85
	v_add_u32_e32 v217, 0x7c000, v216
	global_store_dwordx4 v217, v[180:183], s[94:95] offset:256
	s_waitcnt vmcnt(15)
; __device__ __forceinline__ unsigned pk2(float lo, float hi) { f32x2 v = {lo, hi}; bf16x2_t b = __builtin_convertvector(v, bf16x2_t); return __builtin_bit_cast(unsigned, b); }
; __device__ __forceinline__ float sigm(float x) { return __builtin_amdgcn_rcpf(1.f + fexp(-x)); }
;     __device__ __forceinline__ void operator()(const f32x4 (&acc)[2][2][4][2], const Unit& u, int wr, int wc, int fr, int fq) const {
;     ...
;                         for (int e = 0; e < 8; ++e) o[e] = ma[e] + acc[ai][bj][m][e >> 2][e & 3] * sigm(mb[e]);
;                     } else {
; #pragma unroll
;                         for (int e = 0; e < 8; ++e) o[e] = acc[ai][bj][m][e >> 2][e & 3] * sigm(ma[e]);
;                     }
;                     u32x4 w; w.x = pk2(o[0], o[1]); w.y = pk2(o[2], o[3]); w.z = pk2(o[4], o[5]); w.w = pk2(o[6], o[7]);
;                     *(u32x4*)(roww + C_MA + bj * HALF) = w;
	v_lshlrev_b32_e32 v218, 16, v184
	v_and_b32_e32 v219, 0xffff0000, v184
	v_lshlrev_b32_e32 v220, 16, v185
	v_and_b32_e32 v221, 0xffff0000, v185
	v_lshlrev_b32_e32 v222, 16, v186
	v_and_b32_e32 v223, 0xffff0000, v186
	v_lshlrev_b32_e32 v224, 16, v187
	v_and_b32_e32 v225, 0xffff0000, v187
	v_pk_add_f32 v[78:79], v[78:79], v[218:219]
	v_pk_add_f32 v[80:81], v[80:81], v[220:221]
	v_pk_add_f32 v[74:75], v[74:75], v[222:223]
	v_pk_add_f32 v[76:77], v[76:77], v[224:225]
	v_cvt_pk_bf16_f32 v184, v78, v79
	v_cvt_pk_bf16_f32 v185, v80, v81
	v_cvt_pk_bf16_f32 v186, v74, v75
	v_cvt_pk_bf16_f32 v187, v76, v77
	v_add_u32_e32 v217, 0xba000, v216
	global_store_dwordx4 v217, v[184:187], s[94:95]
	s_waitcnt vmcnt(15)
	v_lshlrev_b32_e32 v218, 16, v188
	v_and_b32_e32 v219, 0xffff0000, v188
	v_lshlrev_b32_e32 v220, 16, v189
	v_and_b32_e32 v221, 0xffff0000, v189
	v_lshlrev_b32_e32 v222, 16, v190
	v_and_b32_e32 v223, 0xffff0000, v190
	v_lshlrev_b32_e32 v224, 16, v191
	v_and_b32_e32 v225, 0xffff0000, v191
	v_pk_add_f32 v[70:71], v[70:71], v[218:219]
	v_pk_add_f32 v[72:73], v[72:73], v[220:221]
	v_pk_add_f32 v[66:67], v[66:67], v[222:223]
	v_pk_add_f32 v[68:69], v[68:69], v[224:225]
	v_cvt_pk_bf16_f32 v188, v70, v71
	v_cvt_pk_bf16_f32 v189, v72, v73
	v_cvt_pk_bf16_f32 v190, v66, v67
	v_cvt_pk_bf16_f32 v191, v68, v69
	v_add_u32_e32 v217, 0xba000, v216
	global_store_dwordx4 v217, v[188:191], s[94:95] offset:256
	s_waitcnt vmcnt(15)
	v_lshlrev_b32_e32 v218, 16, v192
	v_and_b32_e32 v219, 0xffff0000, v192
	v_lshlrev_b32_e32 v220, 16, v193
	v_and_b32_e32 v221, 0xffff0000, v193
	v_lshlrev_b32_e32 v222, 16, v194
	v_and_b32_e32 v223, 0xffff0000, v194
	v_lshlrev_b32_e32 v224, 16, v195
	v_and_b32_e32 v225, 0xffff0000, v195
	v_pk_add_f32 v[62:63], v[62:63], v[218:219]
	v_pk_add_f32 v[64:65], v[64:65], v[220:221]
	v_pk_add_f32 v[58:59], v[58:59], v[222:223]
	v_pk_add_f32 v[60:61], v[60:61], v[224:225]
	v_cvt_pk_bf16_f32 v192, v62, v63
	v_cvt_pk_bf16_f32 v193, v64, v65
	v_cvt_pk_bf16_f32 v194, v58, v59
	v_cvt_pk_bf16_f32 v195, v60, v61
	v_add_u32_e32 v217, 0x1f0000, v216
	global_store_dwordx4 v217, v[192:195], s[94:95]
	s_waitcnt vmcnt(15)
	v_lshlrev_b32_e32 v218, 16, v196
	v_and_b32_e32 v219, 0xffff0000, v196
	v_lshlrev_b32_e32 v220, 16, v197
	v_and_b32_e32 v221, 0xffff0000, v197
	v_lshlrev_b32_e32 v222, 16, v198
	v_and_b32_e32 v223, 0xffff0000, v198
	v_lshlrev_b32_e32 v224, 16, v199
	v_and_b32_e32 v225, 0xffff0000, v199
	v_pk_add_f32 v[54:55], v[54:55], v[218:219]
	v_pk_add_f32 v[56:57], v[56:57], v[220:221]
	v_pk_add_f32 v[50:51], v[50:51], v[222:223]
	v_pk_add_f32 v[52:53], v[52:53], v[224:225]
	v_cvt_pk_bf16_f32 v196, v54, v55
	v_cvt_pk_bf16_f32 v197, v56, v57
	v_cvt_pk_bf16_f32 v198, v50, v51
	v_cvt_pk_bf16_f32 v199, v52, v53
	v_add_u32_e32 v217, 0x1f0000, v216
	global_store_dwordx4 v217, v[196:199], s[94:95] offset:256
	s_waitcnt vmcnt(15)
	v_lshlrev_b32_e32 v218, 16, v200
	v_and_b32_e32 v219, 0xffff0000, v200
	v_lshlrev_b32_e32 v220, 16, v201
	v_and_b32_e32 v221, 0xffff0000, v201
	v_lshlrev_b32_e32 v222, 16, v202
	v_and_b32_e32 v223, 0xffff0000, v202
	v_lshlrev_b32_e32 v224, 16, v203
	v_and_b32_e32 v225, 0xffff0000, v203
	v_pk_add_f32 v[46:47], v[46:47], v[218:219]
	v_pk_add_f32 v[48:49], v[48:49], v[220:221]
	v_pk_add_f32 v[42:43], v[42:43], v[222:223]
	v_pk_add_f32 v[44:45], v[44:45], v[224:225]
	v_cvt_pk_bf16_f32 v200, v46, v47
	v_cvt_pk_bf16_f32 v201, v48, v49
	v_cvt_pk_bf16_f32 v202, v42, v43
	v_cvt_pk_bf16_f32 v203, v44, v45
	v_add_u32_e32 v217, 0x22e000, v216
	global_store_dwordx4 v217, v[200:203], s[94:95]
	s_waitcnt vmcnt(15)
	v_lshlrev_b32_e32 v218, 16, v204
	v_and_b32_e32 v219, 0xffff0000, v204
	v_lshlrev_b32_e32 v220, 16, v205
	v_and_b32_e32 v221, 0xffff0000, v205
	v_lshlrev_b32_e32 v222, 16, v206
	v_and_b32_e32 v223, 0xffff0000, v206
	v_lshlrev_b32_e32 v224, 16, v207
	v_and_b32_e32 v225, 0xffff0000, v207
	v_pk_add_f32 v[38:39], v[38:39], v[218:219]
	v_pk_add_f32 v[40:41], v[40:41], v[220:221]
	v_pk_add_f32 v[34:35], v[34:35], v[222:223]
	v_pk_add_f32 v[36:37], v[36:37], v[224:225]
	v_cvt_pk_bf16_f32 v204, v38, v39
	v_cvt_pk_bf16_f32 v205, v40, v41
	v_cvt_pk_bf16_f32 v206, v34, v35
	v_cvt_pk_bf16_f32 v207, v36, v37
	v_add_u32_e32 v217, 0x22e000, v216
	global_store_dwordx4 v217, v[204:207], s[94:95] offset:256
	s_waitcnt vmcnt(15)
	v_lshlrev_b32_e32 v218, 16, v130
	v_and_b32_e32 v219, 0xffff0000, v130
	v_lshlrev_b32_e32 v220, 16, v131
	v_and_b32_e32 v221, 0xffff0000, v131
	v_lshlrev_b32_e32 v222, 16, v132
	v_and_b32_e32 v223, 0xffff0000, v132
	v_lshlrev_b32_e32 v224, 16, v133
	v_and_b32_e32 v225, 0xffff0000, v133
	v_pk_add_f32 v[30:31], v[30:31], v[218:219]
	v_pk_add_f32 v[32:33], v[32:33], v[220:221]
	v_pk_add_f32 v[26:27], v[26:27], v[222:223]
	v_pk_add_f32 v[28:29], v[28:29], v[224:225]
	v_cvt_pk_bf16_f32 v130, v30, v31
	v_cvt_pk_bf16_f32 v131, v32, v33
	v_cvt_pk_bf16_f32 v132, v26, v27
	v_cvt_pk_bf16_f32 v133, v28, v29
	v_add_u32_e32 v217, 0x26c000, v216
	global_store_dwordx4 v217, v[130:133], s[94:95]
	s_waitcnt vmcnt(15)
	v_lshlrev_b32_e32 v218, 16, v134
	v_and_b32_e32 v219, 0xffff0000, v134
	v_lshlrev_b32_e32 v220, 16, v135
	v_and_b32_e32 v221, 0xffff0000, v135
	v_lshlrev_b32_e32 v222, 16, v136
	v_and_b32_e32 v223, 0xffff0000, v136
	v_lshlrev_b32_e32 v224, 16, v137
	v_and_b32_e32 v225, 0xffff0000, v137
	v_pk_add_f32 v[22:23], v[22:23], v[218:219]
	v_pk_add_f32 v[24:25], v[24:25], v[220:221]
	v_pk_add_f32 v[18:19], v[18:19], v[222:223]
	v_pk_add_f32 v[20:21], v[20:21], v[224:225]
	v_cvt_pk_bf16_f32 v134, v22, v23
	v_cvt_pk_bf16_f32 v135, v24, v25
	v_cvt_pk_bf16_f32 v136, v18, v19
	v_cvt_pk_bf16_f32 v137, v20, v21
	v_add_u32_e32 v217, 0x26c000, v216
	global_store_dwordx4 v217, v[134:137], s[94:95] offset:256
	s_waitcnt vmcnt(15)
; __device__ __forceinline__ unsigned pk2(float lo, float hi) { f32x2 v = {lo, hi}; bf16x2_t b = __builtin_convertvector(v, bf16x2_t); return __builtin_bit_cast(unsigned, b); }
; __device__ __forceinline__ float sigm(float x) { return __builtin_amdgcn_rcpf(1.f + fexp(-x)); }
;     __device__ __forceinline__ void operator()(const f32x4 (&acc)[2][2][4][2], const Unit& u, int wr, int wc, int fr, int fq) const {
;     ...
; #pragma unroll
;                         for (int e = 0; e < 8; ++e) o[e] = acc[ai][bj][m][e >> 2][e & 3] * sigm(ma[e]);
;                     }
;                     u32x4 w; w.x = pk2(o[0], o[1]); w.y = pk2(o[2], o[3]); w.z = pk2(o[4], o[5]); w.w = pk2(o[6], o[7]);
;                     *(u32x4*)(roww + C_MA + bj * HALF) = w;
	v_lshlrev_b32_e32 v218, 16, v148
	v_and_b32_e32 v219, 0xffff0000, v148
	v_lshlrev_b32_e32 v220, 16, v149
	v_and_b32_e32 v221, 0xffff0000, v149
	v_lshlrev_b32_e32 v222, 16, v150
	v_and_b32_e32 v223, 0xffff0000, v150
	v_lshlrev_b32_e32 v224, 16, v151
	v_and_b32_e32 v225, 0xffff0000, v151
	v_pk_add_f32 v[14:15], v[14:15], v[218:219]
	v_pk_add_f32 v[16:17], v[16:17], v[220:221]
	v_pk_add_f32 v[10:11], v[10:11], v[222:223]
	v_pk_add_f32 v[12:13], v[12:13], v[224:225]
	v_cvt_pk_bf16_f32 v148, v14, v15
	v_cvt_pk_bf16_f32 v149, v16, v17
	v_cvt_pk_bf16_f32 v150, v10, v11
	v_cvt_pk_bf16_f32 v151, v12, v13
	v_add_u32_e32 v217, 0x2aa000, v216
	global_store_dwordx4 v217, v[148:151], s[94:95]
	s_waitcnt vmcnt(15)
	v_lshlrev_b32_e32 v218, 16, v152
	v_and_b32_e32 v219, 0xffff0000, v152
	v_lshlrev_b32_e32 v220, 16, v153
	v_and_b32_e32 v221, 0xffff0000, v153
	v_lshlrev_b32_e32 v222, 16, v154
	v_and_b32_e32 v223, 0xffff0000, v154
	v_lshlrev_b32_e32 v224, 16, v155
	v_and_b32_e32 v225, 0xffff0000, v155
	v_pk_add_f32 v[6:7], v[6:7], v[218:219]
	v_pk_add_f32 v[8:9], v[8:9], v[220:221]
	v_pk_add_f32 v[2:3], v[2:3], v[222:223]
	v_pk_add_f32 v[4:5], v[4:5], v[224:225]
	v_cvt_pk_bf16_f32 v152, v6, v7
	v_cvt_pk_bf16_f32 v153, v8, v9
	v_cvt_pk_bf16_f32 v154, v2, v3
	v_cvt_pk_bf16_f32 v155, v4, v5
	v_add_u32_e32 v217, 0x2aa000, v216
	global_store_dwordx4 v217, v[152:155], s[94:95] offset:256
	s_branch .LBB0_49
.Lbp_sel0:
	global_load_dwordx4 v[160:163], v216, s[94:95]
	global_load_dwordx4 v[164:167], v216, s[94:95] offset:256
	v_add_u32_e32 v218, 0x3e000, v216
	global_load_dwordx4 v[168:171], v218, s[94:95]
	global_load_dwordx4 v[172:175], v218, s[94:95] offset:256
	v_add_u32_e32 v217, 0x7c000, v216
	global_load_dwordx4 v[176:179], v217, s[94:95]
	global_load_dwordx4 v[180:183], v217, s[94:95] offset:256
	v_add_u32_e32 v218, 0xba000, v216
	global_load_dwordx4 v[184:187], v218, s[94:95]
	global_load_dwordx4 v[188:191], v218, s[94:95] offset:256
	v_add_u32_e32 v217, 0x1f0000, v216
	global_load_dwordx4 v[192:195], v217, s[94:95]
	global_load_dwordx4 v[196:199], v217, s[94:95] offset:256
	v_add_u32_e32 v218, 0x22e000, v216
	global_load_dwordx4 v[200:203], v218, s[94:95]
	global_load_dwordx4 v[204:207], v218, s[94:95] offset:256
	v_add_u32_e32 v217, 0x26c000, v216
	global_load_dwordx4 v[130:133], v217, s[94:95]
	global_load_dwordx4 v[134:137], v217, s[94:95] offset:256
	v_add_u32_e32 v218, 0x2aa000, v216
	global_load_dwordx4 v[148:151], v218, s[94:95]
	global_load_dwordx4 v[152:155], v218, s[94:95] offset:256
	s_waitcnt vmcnt(15)
	v_lshlrev_b32_e32 v218, 16, v160
	v_and_b32_e32 v219, 0xffff0000, v160
	v_lshlrev_b32_e32 v220, 16, v161
	v_and_b32_e32 v221, 0xffff0000, v161
	v_lshlrev_b32_e32 v222, 16, v162
	v_and_b32_e32 v223, 0xffff0000, v162
	v_lshlrev_b32_e32 v224, 16, v163
	v_and_b32_e32 v225, 0xffff0000, v163
	v_mul_f32_e32 v218, 0xbfb8aa3b, v218
	v_mul_f32_e32 v219, 0xbfb8aa3b, v219
	v_mul_f32_e32 v220, 0xbfb8aa3b, v220
	v_mul_f32_e32 v221, 0xbfb8aa3b, v221
	v_mul_f32_e32 v222, 0xbfb8aa3b, v222
	v_mul_f32_e32 v223, 0xbfb8aa3b, v223
	v_mul_f32_e32 v224, 0xbfb8aa3b, v224
	v_mul_f32_e32 v225, 0xbfb8aa3b, v225
	v_exp_f32_e32 v218, v218
	v_exp_f32_e32 v219, v219
	v_exp_f32_e32 v220, v220
	v_exp_f32_e32 v221, v221
	v_exp_f32_e32 v222, v222
	v_exp_f32_e32 v223, v223
	v_exp_f32_e32 v224, v224
	v_exp_f32_e32 v225, v225
	v_add_f32_e32 v218, 1.0, v218
	v_add_f32_e32 v219, 1.0, v219
	v_add_f32_e32 v220, 1.0, v220
	v_add_f32_e32 v221, 1.0, v221
	v_add_f32_e32 v222, 1.0, v222
	v_add_f32_e32 v223, 1.0, v223
	v_add_f32_e32 v224, 1.0, v224
	v_add_f32_e32 v225, 1.0, v225
	v_rcp_f32_e32 v218, v218
	v_rcp_f32_e32 v219, v219
	v_rcp_f32_e32 v220, v220
	v_rcp_f32_e32 v221, v221
	v_rcp_f32_e32 v222, v222
	v_rcp_f32_e32 v223, v223
	v_rcp_f32_e32 v224, v224
	v_rcp_f32_e32 v225, v225
	v_pk_mul_f32 v[126:127], v[126:127], v[218:219]
	v_pk_mul_f32 v[128:129], v[128:129], v[220:221]
	v_pk_mul_f32 v[122:123], v[122:123], v[222:223]
	v_pk_mul_f32 v[124:125], v[124:125], v[224:225]
	v_cvt_pk_bf16_f32 v160, v126, v127
	v_cvt_pk_bf16_f32 v161, v128, v129
	v_cvt_pk_bf16_f32 v162, v122, v123
	v_cvt_pk_bf16_f32 v163, v124, v125
	global_store_dwordx4 v216, v[160:163], s[94:95]
	s_waitcnt vmcnt(15)
	v_lshlrev_b32_e32 v218, 16, v164
	v_and_b32_e32 v219, 0xffff0000, v164
	v_lshlrev_b32_e32 v220, 16, v165
	v_and_b32_e32 v221, 0xffff0000, v165
	v_lshlrev_b32_e32 v222, 16, v166
	v_and_b32_e32 v223, 0xffff0000, v166
	v_lshlrev_b32_e32 v224, 16, v167
	v_and_b32_e32 v225, 0xffff0000, v167
	v_mul_f32_e32 v218, 0xbfb8aa3b, v218
	v_mul_f32_e32 v219, 0xbfb8aa3b, v219
	v_mul_f32_e32 v220, 0xbfb8aa3b, v220
	v_mul_f32_e32 v221, 0xbfb8aa3b, v221
	v_mul_f32_e32 v222, 0xbfb8aa3b, v222
	v_mul_f32_e32 v223, 0xbfb8aa3b, v223
	v_mul_f32_e32 v224, 0xbfb8aa3b, v224
	v_mul_f32_e32 v225, 0xbfb8aa3b, v225
	v_exp_f32_e32 v218, v218
	v_exp_f32_e32 v219, v219
	v_exp_f32_e32 v220, v220
	v_exp_f32_e32 v221, v221
	v_exp_f32_e32 v222, v222
	v_exp_f32_e32 v223, v223
	v_exp_f32_e32 v224, v224
	v_exp_f32_e32 v225, v225
	v_add_f32_e32 v218, 1.0, v218
	v_add_f32_e32 v219, 1.0, v219
	v_add_f32_e32 v220, 1.0, v220
	v_add_f32_e32 v221, 1.0, v221
	v_add_f32_e32 v222, 1.0, v222
	v_add_f32_e32 v223, 1.0, v223
	v_add_f32_e32 v224, 1.0, v224
	v_add_f32_e32 v225, 1.0, v225
	v_rcp_f32_e32 v218, v218
	v_rcp_f32_e32 v219, v219
	v_rcp_f32_e32 v220, v220
	v_rcp_f32_e32 v221, v221
	v_rcp_f32_e32 v222, v222
	v_rcp_f32_e32 v223, v223
	v_rcp_f32_e32 v224, v224
	v_rcp_f32_e32 v225, v225
	v_pk_mul_f32 v[118:119], v[118:119], v[218:219]
	v_pk_mul_f32 v[120:121], v[120:121], v[220:221]
	v_pk_mul_f32 v[114:115], v[114:115], v[222:223]
	v_pk_mul_f32 v[116:117], v[116:117], v[224:225]
	v_cvt_pk_bf16_f32 v164, v118, v119
	v_cvt_pk_bf16_f32 v165, v120, v121
	v_cvt_pk_bf16_f32 v166, v114, v115
	v_cvt_pk_bf16_f32 v167, v116, v117
	global_store_dwordx4 v216, v[164:167], s[94:95] offset:256
	s_waitcnt vmcnt(15)
; __device__ __forceinline__ unsigned pk2(float lo, float hi) { f32x2 v = {lo, hi}; bf16x2_t b = __builtin_convertvector(v, bf16x2_t); return __builtin_bit_cast(unsigned, b); }
; __device__ __forceinline__ float sigm(float x) { return __builtin_amdgcn_rcpf(1.f + fexp(-x)); }
;     __device__ __forceinline__ void operator()(const f32x4 (&acc)[2][2][4][2], const Unit& u, int wr, int wc, int fr, int fq) const {
;     ...
; #pragma unroll
;                         for (int e = 0; e < 8; ++e) o[e] = acc[ai][bj][m][e >> 2][e & 3] * sigm(ma[e]);
;                     }
;                     u32x4 w; w.x = pk2(o[0], o[1]); w.y = pk2(o[2], o[3]); w.z = pk2(o[4], o[5]); w.w = pk2(o[6], o[7]);
;                     *(u32x4*)(roww + C_MA + bj * HALF) = w;
	v_lshlrev_b32_e32 v218, 16, v168
	v_and_b32_e32 v219, 0xffff0000, v168
	v_lshlrev_b32_e32 v220, 16, v169
	v_and_b32_e32 v221, 0xffff0000, v169
	v_lshlrev_b32_e32 v222, 16, v170
	v_and_b32_e32 v223, 0xffff0000, v170
	v_lshlrev_b32_e32 v224, 16, v171
	v_and_b32_e32 v225, 0xffff0000, v171
	v_mul_f32_e32 v218, 0xbfb8aa3b, v218
	v_mul_f32_e32 v219, 0xbfb8aa3b, v219
	v_mul_f32_e32 v220, 0xbfb8aa3b, v220
	v_mul_f32_e32 v221, 0xbfb8aa3b, v221
	v_mul_f32_e32 v222, 0xbfb8aa3b, v222
	v_mul_f32_e32 v223, 0xbfb8aa3b, v223
	v_mul_f32_e32 v224, 0xbfb8aa3b, v224
	v_mul_f32_e32 v225, 0xbfb8aa3b, v225
	v_exp_f32_e32 v218, v218
	v_exp_f32_e32 v219, v219
	v_exp_f32_e32 v220, v220
	v_exp_f32_e32 v221, v221
	v_exp_f32_e32 v222, v222
	v_exp_f32_e32 v223, v223
	v_exp_f32_e32 v224, v224
	v_exp_f32_e32 v225, v225
	v_add_f32_e32 v218, 1.0, v218
	v_add_f32_e32 v219, 1.0, v219
	v_add_f32_e32 v220, 1.0, v220
	v_add_f32_e32 v221, 1.0, v221
	v_add_f32_e32 v222, 1.0, v222
	v_add_f32_e32 v223, 1.0, v223
	v_add_f32_e32 v224, 1.0, v224
	v_add_f32_e32 v225, 1.0, v225
	v_rcp_f32_e32 v218, v218
	v_rcp_f32_e32 v219, v219
	v_rcp_f32_e32 v220, v220
	v_rcp_f32_e32 v221, v221
	v_rcp_f32_e32 v222, v222
	v_rcp_f32_e32 v223, v223
	v_rcp_f32_e32 v224, v224
	v_rcp_f32_e32 v225, v225
	v_pk_mul_f32 v[110:111], v[110:111], v[218:219]
	v_pk_mul_f32 v[112:113], v[112:113], v[220:221]
	v_pk_mul_f32 v[106:107], v[106:107], v[222:223]
	v_pk_mul_f32 v[108:109], v[108:109], v[224:225]
	v_cvt_pk_bf16_f32 v168, v110, v111
	v_cvt_pk_bf16_f32 v169, v112, v113
	v_cvt_pk_bf16_f32 v170, v106, v107
	v_cvt_pk_bf16_f32 v171, v108, v109
	v_add_u32_e32 v217, 0x3e000, v216
	global_store_dwordx4 v217, v[168:171], s[94:95]
	s_waitcnt vmcnt(15)
	v_lshlrev_b32_e32 v218, 16, v172
	v_and_b32_e32 v219, 0xffff0000, v172
	v_lshlrev_b32_e32 v220, 16, v173
	v_and_b32_e32 v221, 0xffff0000, v173
	v_lshlrev_b32_e32 v222, 16, v174
	v_and_b32_e32 v223, 0xffff0000, v174
	v_lshlrev_b32_e32 v224, 16, v175
	v_and_b32_e32 v225, 0xffff0000, v175
	v_mul_f32_e32 v218, 0xbfb8aa3b, v218
	v_mul_f32_e32 v219, 0xbfb8aa3b, v219
	v_mul_f32_e32 v220, 0xbfb8aa3b, v220
	v_mul_f32_e32 v221, 0xbfb8aa3b, v221
	v_mul_f32_e32 v222, 0xbfb8aa3b, v222
	v_mul_f32_e32 v223, 0xbfb8aa3b, v223
	v_mul_f32_e32 v224, 0xbfb8aa3b, v224
	v_mul_f32_e32 v225, 0xbfb8aa3b, v225
	v_exp_f32_e32 v218, v218
	v_exp_f32_e32 v219, v219
	v_exp_f32_e32 v220, v220
	v_exp_f32_e32 v221, v221
	v_exp_f32_e32 v222, v222
	v_exp_f32_e32 v223, v223
	v_exp_f32_e32 v224, v224
	v_exp_f32_e32 v225, v225
	v_add_f32_e32 v218, 1.0, v218
	v_add_f32_e32 v219, 1.0, v219
	v_add_f32_e32 v220, 1.0, v220
	v_add_f32_e32 v221, 1.0, v221
	v_add_f32_e32 v222, 1.0, v222
	v_add_f32_e32 v223, 1.0, v223
	v_add_f32_e32 v224, 1.0, v224
	v_add_f32_e32 v225, 1.0, v225
	v_rcp_f32_e32 v218, v218
	v_rcp_f32_e32 v219, v219
	v_rcp_f32_e32 v220, v220
	v_rcp_f32_e32 v221, v221
	v_rcp_f32_e32 v222, v222
	v_rcp_f32_e32 v223, v223
	v_rcp_f32_e32 v224, v224
	v_rcp_f32_e32 v225, v225
	v_pk_mul_f32 v[102:103], v[102:103], v[218:219]
	v_pk_mul_f32 v[104:105], v[104:105], v[220:221]
	v_pk_mul_f32 v[98:99], v[98:99], v[222:223]
	v_pk_mul_f32 v[100:101], v[100:101], v[224:225]
	v_cvt_pk_bf16_f32 v172, v102, v103
	v_cvt_pk_bf16_f32 v173, v104, v105
	v_cvt_pk_bf16_f32 v174, v98, v99
	v_cvt_pk_bf16_f32 v175, v100, v101
	v_add_u32_e32 v217, 0x3e000, v216
	global_store_dwordx4 v217, v[172:175], s[94:95] offset:256
	s_waitcnt vmcnt(15)
	v_lshlrev_b32_e32 v218, 16, v176
	v_and_b32_e32 v219, 0xffff0000, v176
	v_lshlrev_b32_e32 v220, 16, v177
	v_and_b32_e32 v221, 0xffff0000, v177
	v_lshlrev_b32_e32 v222, 16, v178
	v_and_b32_e32 v223, 0xffff0000, v178
	v_lshlrev_b32_e32 v224, 16, v179
	v_and_b32_e32 v225, 0xffff0000, v179
	v_mul_f32_e32 v218, 0xbfb8aa3b, v218
	v_mul_f32_e32 v219, 0xbfb8aa3b, v219
	v_mul_f32_e32 v220, 0xbfb8aa3b, v220
	v_mul_f32_e32 v221, 0xbfb8aa3b, v221
	v_mul_f32_e32 v222, 0xbfb8aa3b, v222
	v_mul_f32_e32 v223, 0xbfb8aa3b, v223
	v_mul_f32_e32 v224, 0xbfb8aa3b, v224
	v_mul_f32_e32 v225, 0xbfb8aa3b, v225
	v_exp_f32_e32 v218, v218
	v_exp_f32_e32 v219, v219
	v_exp_f32_e32 v220, v220
	v_exp_f32_e32 v221, v221
	v_exp_f32_e32 v222, v222
	v_exp_f32_e32 v223, v223
	v_exp_f32_e32 v224, v224
	v_exp_f32_e32 v225, v225
	v_add_f32_e32 v218, 1.0, v218
	v_add_f32_e32 v219, 1.0, v219
	v_add_f32_e32 v220, 1.0, v220
	v_add_f32_e32 v221, 1.0, v221
	v_add_f32_e32 v222, 1.0, v222
	v_add_f32_e32 v223, 1.0, v223
	v_add_f32_e32 v224, 1.0, v224
	v_add_f32_e32 v225, 1.0, v225
	v_rcp_f32_e32 v218, v218
	v_rcp_f32_e32 v219, v219
	v_rcp_f32_e32 v220, v220
	v_rcp_f32_e32 v221, v221
	v_rcp_f32_e32 v222, v222
	v_rcp_f32_e32 v223, v223
	v_rcp_f32_e32 v224, v224
	v_rcp_f32_e32 v225, v225
	v_pk_mul_f32 v[94:95], v[94:95], v[218:219]
	v_pk_mul_f32 v[96:97], v[96:97], v[220:221]
	v_pk_mul_f32 v[90:91], v[90:91], v[222:223]
	v_pk_mul_f32 v[92:93], v[92:93], v[224:225]
	v_cvt_pk_bf16_f32 v176, v94, v95
	v_cvt_pk_bf16_f32 v177, v96, v97
	v_cvt_pk_bf16_f32 v178, v90, v91
	v_cvt_pk_bf16_f32 v179, v92, v93
	v_add_u32_e32 v217, 0x7c000, v216
	global_store_dwordx4 v217, v[176:179], s[94:95]
	s_waitcnt vmcnt(15)
; __device__ __forceinline__ unsigned pk2(float lo, float hi) { f32x2 v = {lo, hi}; bf16x2_t b = __builtin_convertvector(v, bf16x2_t); return __builtin_bit_cast(unsigned, b); }
; __device__ __forceinline__ float sigm(float x) { return __builtin_amdgcn_rcpf(1.f + fexp(-x)); }
;     __device__ __forceinline__ void operator()(const f32x4 (&acc)[2][2][4][2], const Unit& u, int wr, int wc, int fr, int fq) const {
;     ...
; #pragma unroll
;                         for (int e = 0; e < 8; ++e) o[e] = acc[ai][bj][m][e >> 2][e & 3] * sigm(ma[e]);
;                     }
;                     u32x4 w; w.x = pk2(o[0], o[1]); w.y = pk2(o[2], o[3]); w.z = pk2(o[4], o[5]); w.w = pk2(o[6], o[7]);
;                     *(u32x4*)(roww + C_MA + bj * HALF) = w;
	v_lshlrev_b32_e32 v218, 16, v180
	v_and_b32_e32 v219, 0xffff0000, v180
	v_lshlrev_b32_e32 v220, 16, v181
	v_and_b32_e32 v221, 0xffff0000, v181
	v_lshlrev_b32_e32 v222, 16, v182
	v_and_b32_e32 v223, 0xffff0000, v182
	v_lshlrev_b32_e32 v224, 16, v183
	v_and_b32_e32 v225, 0xffff0000, v183
	v_mul_f32_e32 v218, 0xbfb8aa3b, v218
	v_mul_f32_e32 v219, 0xbfb8aa3b, v219
	v_mul_f32_e32 v220, 0xbfb8aa3b, v220
	v_mul_f32_e32 v221, 0xbfb8aa3b, v221
	v_mul_f32_e32 v222, 0xbfb8aa3b, v222
	v_mul_f32_e32 v223, 0xbfb8aa3b, v223
	v_mul_f32_e32 v224, 0xbfb8aa3b, v224
	v_mul_f32_e32 v225, 0xbfb8aa3b, v225
	v_exp_f32_e32 v218, v218
	v_exp_f32_e32 v219, v219
	v_exp_f32_e32 v220, v220
	v_exp_f32_e32 v221, v221
	v_exp_f32_e32 v222, v222
	v_exp_f32_e32 v223, v223
	v_exp_f32_e32 v224, v224
	v_exp_f32_e32 v225, v225
	v_add_f32_e32 v218, 1.0, v218
	v_add_f32_e32 v219, 1.0, v219
	v_add_f32_e32 v220, 1.0, v220
	v_add_f32_e32 v221, 1.0, v221
	v_add_f32_e32 v222, 1.0, v222
	v_add_f32_e32 v223, 1.0, v223
	v_add_f32_e32 v224, 1.0, v224
	v_add_f32_e32 v225, 1.0, v225
	v_rcp_f32_e32 v218, v218
	v_rcp_f32_e32 v219, v219
	v_rcp_f32_e32 v220, v220
	v_rcp_f32_e32 v221, v221
	v_rcp_f32_e32 v222, v222
	v_rcp_f32_e32 v223, v223
	v_rcp_f32_e32 v224, v224
	v_rcp_f32_e32 v225, v225
	v_pk_mul_f32 v[86:87], v[86:87], v[218:219]
	v_pk_mul_f32 v[88:89], v[88:89], v[220:221]
	v_pk_mul_f32 v[82:83], v[82:83], v[222:223]
	v_pk_mul_f32 v[84:85], v[84:85], v[224:225]
	v_cvt_pk_bf16_f32 v180, v86, v87
	v_cvt_pk_bf16_f32 v181, v88, v89
	v_cvt_pk_bf16_f32 v182, v82, v83
	v_cvt_pk_bf16_f32 v183, v84, v85
	v_add_u32_e32 v217, 0x7c000, v216
	global_store_dwordx4 v217, v[180:183], s[94:95] offset:256
	s_waitcnt vmcnt(15)
	v_lshlrev_b32_e32 v218, 16, v184
	v_and_b32_e32 v219, 0xffff0000, v184
	v_lshlrev_b32_e32 v220, 16, v185
	v_and_b32_e32 v221, 0xffff0000, v185
	v_lshlrev_b32_e32 v222, 16, v186
	v_and_b32_e32 v223, 0xffff0000, v186
	v_lshlrev_b32_e32 v224, 16, v187
	v_and_b32_e32 v225, 0xffff0000, v187
	v_mul_f32_e32 v218, 0xbfb8aa3b, v218
	v_mul_f32_e32 v219, 0xbfb8aa3b, v219
	v_mul_f32_e32 v220, 0xbfb8aa3b, v220
	v_mul_f32_e32 v221, 0xbfb8aa3b, v221
	v_mul_f32_e32 v222, 0xbfb8aa3b, v222
	v_mul_f32_e32 v223, 0xbfb8aa3b, v223
	v_mul_f32_e32 v224, 0xbfb8aa3b, v224
	v_mul_f32_e32 v225, 0xbfb8aa3b, v225
	v_exp_f32_e32 v218, v218
	v_exp_f32_e32 v219, v219
	v_exp_f32_e32 v220, v220
	v_exp_f32_e32 v221, v221
	v_exp_f32_e32 v222, v222
	v_exp_f32_e32 v223, v223
	v_exp_f32_e32 v224, v224
	v_exp_f32_e32 v225, v225
	v_add_f32_e32 v218, 1.0, v218
	v_add_f32_e32 v219, 1.0, v219
	v_add_f32_e32 v220, 1.0, v220
	v_add_f32_e32 v221, 1.0, v221
	v_add_f32_e32 v222, 1.0, v222
	v_add_f32_e32 v223, 1.0, v223
	v_add_f32_e32 v224, 1.0, v224
	v_add_f32_e32 v225, 1.0, v225
	v_rcp_f32_e32 v218, v218
	v_rcp_f32_e32 v219, v219
	v_rcp_f32_e32 v220, v220
	v_rcp_f32_e32 v221, v221
	v_rcp_f32_e32 v222, v222
	v_rcp_f32_e32 v223, v223
	v_rcp_f32_e32 v224, v224
	v_rcp_f32_e32 v225, v225
	v_pk_mul_f32 v[78:79], v[78:79], v[218:219]
	v_pk_mul_f32 v[80:81], v[80:81], v[220:221]
	v_pk_mul_f32 v[74:75], v[74:75], v[222:223]
	v_pk_mul_f32 v[76:77], v[76:77], v[224:225]
	v_cvt_pk_bf16_f32 v184, v78, v79
	v_cvt_pk_bf16_f32 v185, v80, v81
	v_cvt_pk_bf16_f32 v186, v74, v75
	v_cvt_pk_bf16_f32 v187, v76, v77
	v_add_u32_e32 v217, 0xba000, v216
	global_store_dwordx4 v217, v[184:187], s[94:95]
	s_waitcnt vmcnt(15)
	v_lshlrev_b32_e32 v218, 16, v188
	v_and_b32_e32 v219, 0xffff0000, v188
	v_lshlrev_b32_e32 v220, 16, v189
	v_and_b32_e32 v221, 0xffff0000, v189
	v_lshlrev_b32_e32 v222, 16, v190
	v_and_b32_e32 v223, 0xffff0000, v190
	v_lshlrev_b32_e32 v224, 16, v191
	v_and_b32_e32 v225, 0xffff0000, v191
	v_mul_f32_e32 v218, 0xbfb8aa3b, v218
	v_mul_f32_e32 v219, 0xbfb8aa3b, v219
	v_mul_f32_e32 v220, 0xbfb8aa3b, v220
	v_mul_f32_e32 v221, 0xbfb8aa3b, v221
	v_mul_f32_e32 v222, 0xbfb8aa3b, v222
	v_mul_f32_e32 v223, 0xbfb8aa3b, v223
	v_mul_f32_e32 v224, 0xbfb8aa3b, v224
	v_mul_f32_e32 v225, 0xbfb8aa3b, v225
	v_exp_f32_e32 v218, v218
	v_exp_f32_e32 v219, v219
	v_exp_f32_e32 v220, v220
	v_exp_f32_e32 v221, v221
	v_exp_f32_e32 v222, v222
	v_exp_f32_e32 v223, v223
	v_exp_f32_e32 v224, v224
	v_exp_f32_e32 v225, v225
	v_add_f32_e32 v218, 1.0, v218
	v_add_f32_e32 v219, 1.0, v219
	v_add_f32_e32 v220, 1.0, v220
	v_add_f32_e32 v221, 1.0, v221
	v_add_f32_e32 v222, 1.0, v222
	v_add_f32_e32 v223, 1.0, v223
	v_add_f32_e32 v224, 1.0, v224
	v_add_f32_e32 v225, 1.0, v225
	v_rcp_f32_e32 v218, v218
	v_rcp_f32_e32 v219, v219
	v_rcp_f32_e32 v220, v220
	v_rcp_f32_e32 v221, v221
	v_rcp_f32_e32 v222, v222
	v_rcp_f32_e32 v223, v223
	v_rcp_f32_e32 v224, v224
	v_rcp_f32_e32 v225, v225
	v_pk_mul_f32 v[70:71], v[70:71], v[218:219]
	v_pk_mul_f32 v[72:73], v[72:73], v[220:221]
	v_pk_mul_f32 v[66:67], v[66:67], v[222:223]
	v_pk_mul_f32 v[68:69], v[68:69], v[224:225]
	v_cvt_pk_bf16_f32 v188, v70, v71
	v_cvt_pk_bf16_f32 v189, v72, v73
	v_cvt_pk_bf16_f32 v190, v66, v67
	v_cvt_pk_bf16_f32 v191, v68, v69
	v_add_u32_e32 v217, 0xba000, v216
	global_store_dwordx4 v217, v[188:191], s[94:95] offset:256
	s_waitcnt vmcnt(15)
; __device__ __forceinline__ unsigned pk2(float lo, float hi) { f32x2 v = {lo, hi}; bf16x2_t b = __builtin_convertvector(v, bf16x2_t); return __builtin_bit_cast(unsigned, b); }
; __device__ __forceinline__ float sigm(float x) { return __builtin_amdgcn_rcpf(1.f + fexp(-x)); }
;     __device__ __forceinline__ void operator()(const f32x4 (&acc)[2][2][4][2], const Unit& u, int wr, int wc, int fr, int fq) const {
;     ...
; #pragma unroll
;                         for (int e = 0; e < 8; ++e) o[e] = acc[ai][bj][m][e >> 2][e & 3] * sigm(ma[e]);
;                     }
;                     u32x4 w; w.x = pk2(o[0], o[1]); w.y = pk2(o[2], o[3]); w.z = pk2(o[4], o[5]); w.w = pk2(o[6], o[7]);
;                     *(u32x4*)(roww + C_MA + bj * HALF) = w;
	v_lshlrev_b32_e32 v218, 16, v192
	v_and_b32_e32 v219, 0xffff0000, v192
	v_lshlrev_b32_e32 v220, 16, v193
	v_and_b32_e32 v221, 0xffff0000, v193
	v_lshlrev_b32_e32 v222, 16, v194
	v_and_b32_e32 v223, 0xffff0000, v194
	v_lshlrev_b32_e32 v224, 16, v195
	v_and_b32_e32 v225, 0xffff0000, v195
	v_mul_f32_e32 v218, 0xbfb8aa3b, v218
	v_mul_f32_e32 v219, 0xbfb8aa3b, v219
	v_mul_f32_e32 v220, 0xbfb8aa3b, v220
	v_mul_f32_e32 v221, 0xbfb8aa3b, v221
	v_mul_f32_e32 v222, 0xbfb8aa3b, v222
	v_mul_f32_e32 v223, 0xbfb8aa3b, v223
	v_mul_f32_e32 v224, 0xbfb8aa3b, v224
	v_mul_f32_e32 v225, 0xbfb8aa3b, v225
	v_exp_f32_e32 v218, v218
	v_exp_f32_e32 v219, v219
	v_exp_f32_e32 v220, v220
	v_exp_f32_e32 v221, v221
	v_exp_f32_e32 v222, v222
	v_exp_f32_e32 v223, v223
	v_exp_f32_e32 v224, v224
	v_exp_f32_e32 v225, v225
	v_add_f32_e32 v218, 1.0, v218
	v_add_f32_e32 v219, 1.0, v219
	v_add_f32_e32 v220, 1.0, v220
	v_add_f32_e32 v221, 1.0, v221
	v_add_f32_e32 v222, 1.0, v222
	v_add_f32_e32 v223, 1.0, v223
	v_add_f32_e32 v224, 1.0, v224
	v_add_f32_e32 v225, 1.0, v225
	v_rcp_f32_e32 v218, v218
	v_rcp_f32_e32 v219, v219
	v_rcp_f32_e32 v220, v220
	v_rcp_f32_e32 v221, v221
	v_rcp_f32_e32 v222, v222
	v_rcp_f32_e32 v223, v223
	v_rcp_f32_e32 v224, v224
	v_rcp_f32_e32 v225, v225
	v_pk_mul_f32 v[62:63], v[62:63], v[218:219]
	v_pk_mul_f32 v[64:65], v[64:65], v[220:221]
	v_pk_mul_f32 v[58:59], v[58:59], v[222:223]
	v_pk_mul_f32 v[60:61], v[60:61], v[224:225]
	v_cvt_pk_bf16_f32 v192, v62, v63
	v_cvt_pk_bf16_f32 v193, v64, v65
	v_cvt_pk_bf16_f32 v194, v58, v59
	v_cvt_pk_bf16_f32 v195, v60, v61
	v_add_u32_e32 v217, 0x1f0000, v216
	global_store_dwordx4 v217, v[192:195], s[94:95]
	s_waitcnt vmcnt(15)
	v_lshlrev_b32_e32 v218, 16, v196
	v_and_b32_e32 v219, 0xffff0000, v196
	v_lshlrev_b32_e32 v220, 16, v197
	v_and_b32_e32 v221, 0xffff0000, v197
	v_lshlrev_b32_e32 v222, 16, v198
	v_and_b32_e32 v223, 0xffff0000, v198
	v_lshlrev_b32_e32 v224, 16, v199
	v_and_b32_e32 v225, 0xffff0000, v199
	v_mul_f32_e32 v218, 0xbfb8aa3b, v218
	v_mul_f32_e32 v219, 0xbfb8aa3b, v219
	v_mul_f32_e32 v220, 0xbfb8aa3b, v220
	v_mul_f32_e32 v221, 0xbfb8aa3b, v221
	v_mul_f32_e32 v222, 0xbfb8aa3b, v222
	v_mul_f32_e32 v223, 0xbfb8aa3b, v223
	v_mul_f32_e32 v224, 0xbfb8aa3b, v224
	v_mul_f32_e32 v225, 0xbfb8aa3b, v225
	v_exp_f32_e32 v218, v218
	v_exp_f32_e32 v219, v219
	v_exp_f32_e32 v220, v220
	v_exp_f32_e32 v221, v221
	v_exp_f32_e32 v222, v222
	v_exp_f32_e32 v223, v223
	v_exp_f32_e32 v224, v224
	v_exp_f32_e32 v225, v225
	v_add_f32_e32 v218, 1.0, v218
	v_add_f32_e32 v219, 1.0, v219
	v_add_f32_e32 v220, 1.0, v220
	v_add_f32_e32 v221, 1.0, v221
	v_add_f32_e32 v222, 1.0, v222
	v_add_f32_e32 v223, 1.0, v223
	v_add_f32_e32 v224, 1.0, v224
	v_add_f32_e32 v225, 1.0, v225
	v_rcp_f32_e32 v218, v218
	v_rcp_f32_e32 v219, v219
	v_rcp_f32_e32 v220, v220
	v_rcp_f32_e32 v221, v221
	v_rcp_f32_e32 v222, v222
	v_rcp_f32_e32 v223, v223
	v_rcp_f32_e32 v224, v224
	v_rcp_f32_e32 v225, v225
	v_pk_mul_f32 v[54:55], v[54:55], v[218:219]
	v_pk_mul_f32 v[56:57], v[56:57], v[220:221]
	v_pk_mul_f32 v[50:51], v[50:51], v[222:223]
	v_pk_mul_f32 v[52:53], v[52:53], v[224:225]
	v_cvt_pk_bf16_f32 v196, v54, v55
	v_cvt_pk_bf16_f32 v197, v56, v57
	v_cvt_pk_bf16_f32 v198, v50, v51
	v_cvt_pk_bf16_f32 v199, v52, v53
	v_add_u32_e32 v217, 0x1f0000, v216
	global_store_dwordx4 v217, v[196:199], s[94:95] offset:256
	s_waitcnt vmcnt(15)
	v_lshlrev_b32_e32 v218, 16, v200
	v_and_b32_e32 v219, 0xffff0000, v200
	v_lshlrev_b32_e32 v220, 16, v201
	v_and_b32_e32 v221, 0xffff0000, v201
	v_lshlrev_b32_e32 v222, 16, v202
	v_and_b32_e32 v223, 0xffff0000, v202
	v_lshlrev_b32_e32 v224, 16, v203
	v_and_b32_e32 v225, 0xffff0000, v203
	v_mul_f32_e32 v218, 0xbfb8aa3b, v218
	v_mul_f32_e32 v219, 0xbfb8aa3b, v219
	v_mul_f32_e32 v220, 0xbfb8aa3b, v220
	v_mul_f32_e32 v221, 0xbfb8aa3b, v221
	v_mul_f32_e32 v222, 0xbfb8aa3b, v222
	v_mul_f32_e32 v223, 0xbfb8aa3b, v223
	v_mul_f32_e32 v224, 0xbfb8aa3b, v224
	v_mul_f32_e32 v225, 0xbfb8aa3b, v225
	v_exp_f32_e32 v218, v218
	v_exp_f32_e32 v219, v219
	v_exp_f32_e32 v220, v220
	v_exp_f32_e32 v221, v221
	v_exp_f32_e32 v222, v222
	v_exp_f32_e32 v223, v223
	v_exp_f32_e32 v224, v224
	v_exp_f32_e32 v225, v225
	v_add_f32_e32 v218, 1.0, v218
	v_add_f32_e32 v219, 1.0, v219
	v_add_f32_e32 v220, 1.0, v220
	v_add_f32_e32 v221, 1.0, v221
	v_add_f32_e32 v222, 1.0, v222
	v_add_f32_e32 v223, 1.0, v223
	v_add_f32_e32 v224, 1.0, v224
	v_add_f32_e32 v225, 1.0, v225
	v_rcp_f32_e32 v218, v218
	v_rcp_f32_e32 v219, v219
	v_rcp_f32_e32 v220, v220
	v_rcp_f32_e32 v221, v221
	v_rcp_f32_e32 v222, v222
	v_rcp_f32_e32 v223, v223
	v_rcp_f32_e32 v224, v224
	v_rcp_f32_e32 v225, v225
	v_pk_mul_f32 v[46:47], v[46:47], v[218:219]
	v_pk_mul_f32 v[48:49], v[48:49], v[220:221]
	v_pk_mul_f32 v[42:43], v[42:43], v[222:223]
	v_pk_mul_f32 v[44:45], v[44:45], v[224:225]
	v_cvt_pk_bf16_f32 v200, v46, v47
	v_cvt_pk_bf16_f32 v201, v48, v49
	v_cvt_pk_bf16_f32 v202, v42, v43
	v_cvt_pk_bf16_f32 v203, v44, v45
	v_add_u32_e32 v217, 0x22e000, v216
	global_store_dwordx4 v217, v[200:203], s[94:95]
	s_waitcnt vmcnt(15)
; __device__ __forceinline__ unsigned pk2(float lo, float hi) { f32x2 v = {lo, hi}; bf16x2_t b = __builtin_convertvector(v, bf16x2_t); return __builtin_bit_cast(unsigned, b); }
; __device__ __forceinline__ float sigm(float x) { return __builtin_amdgcn_rcpf(1.f + fexp(-x)); }
;     __device__ __forceinline__ void operator()(const f32x4 (&acc)[2][2][4][2], const Unit& u, int wr, int wc, int fr, int fq) const {
;     ...
; #pragma unroll
;                         for (int e = 0; e < 8; ++e) o[e] = acc[ai][bj][m][e >> 2][e & 3] * sigm(ma[e]);
;                     }
;                     u32x4 w; w.x = pk2(o[0], o[1]); w.y = pk2(o[2], o[3]); w.z = pk2(o[4], o[5]); w.w = pk2(o[6], o[7]);
;                     *(u32x4*)(roww + C_MA + bj * HALF) = w;
	v_lshlrev_b32_e32 v218, 16, v204
	v_and_b32_e32 v219, 0xffff0000, v204
	v_lshlrev_b32_e32 v220, 16, v205
	v_and_b32_e32 v221, 0xffff0000, v205
	v_lshlrev_b32_e32 v222, 16, v206
	v_and_b32_e32 v223, 0xffff0000, v206
	v_lshlrev_b32_e32 v224, 16, v207
	v_and_b32_e32 v225, 0xffff0000, v207
	v_mul_f32_e32 v218, 0xbfb8aa3b, v218
	v_mul_f32_e32 v219, 0xbfb8aa3b, v219
	v_mul_f32_e32 v220, 0xbfb8aa3b, v220
	v_mul_f32_e32 v221, 0xbfb8aa3b, v221
	v_mul_f32_e32 v222, 0xbfb8aa3b, v222
	v_mul_f32_e32 v223, 0xbfb8aa3b, v223
	v_mul_f32_e32 v224, 0xbfb8aa3b, v224
	v_mul_f32_e32 v225, 0xbfb8aa3b, v225
	v_exp_f32_e32 v218, v218
	v_exp_f32_e32 v219, v219
	v_exp_f32_e32 v220, v220
	v_exp_f32_e32 v221, v221
	v_exp_f32_e32 v222, v222
	v_exp_f32_e32 v223, v223
	v_exp_f32_e32 v224, v224
	v_exp_f32_e32 v225, v225
	v_add_f32_e32 v218, 1.0, v218
	v_add_f32_e32 v219, 1.0, v219
	v_add_f32_e32 v220, 1.0, v220
	v_add_f32_e32 v221, 1.0, v221
	v_add_f32_e32 v222, 1.0, v222
	v_add_f32_e32 v223, 1.0, v223
	v_add_f32_e32 v224, 1.0, v224
	v_add_f32_e32 v225, 1.0, v225
	v_rcp_f32_e32 v218, v218
	v_rcp_f32_e32 v219, v219
	v_rcp_f32_e32 v220, v220
	v_rcp_f32_e32 v221, v221
	v_rcp_f32_e32 v222, v222
	v_rcp_f32_e32 v223, v223
	v_rcp_f32_e32 v224, v224
	v_rcp_f32_e32 v225, v225
	v_pk_mul_f32 v[38:39], v[38:39], v[218:219]
	v_pk_mul_f32 v[40:41], v[40:41], v[220:221]
	v_pk_mul_f32 v[34:35], v[34:35], v[222:223]
	v_pk_mul_f32 v[36:37], v[36:37], v[224:225]
	v_cvt_pk_bf16_f32 v204, v38, v39
	v_cvt_pk_bf16_f32 v205, v40, v41
	v_cvt_pk_bf16_f32 v206, v34, v35
	v_cvt_pk_bf16_f32 v207, v36, v37
	v_add_u32_e32 v217, 0x22e000, v216
	global_store_dwordx4 v217, v[204:207], s[94:95] offset:256
	s_waitcnt vmcnt(15)
	v_lshlrev_b32_e32 v218, 16, v130
	v_and_b32_e32 v219, 0xffff0000, v130
	v_lshlrev_b32_e32 v220, 16, v131
	v_and_b32_e32 v221, 0xffff0000, v131
	v_lshlrev_b32_e32 v222, 16, v132
	v_and_b32_e32 v223, 0xffff0000, v132
	v_lshlrev_b32_e32 v224, 16, v133
	v_and_b32_e32 v225, 0xffff0000, v133
	v_mul_f32_e32 v218, 0xbfb8aa3b, v218
	v_mul_f32_e32 v219, 0xbfb8aa3b, v219
	v_mul_f32_e32 v220, 0xbfb8aa3b, v220
	v_mul_f32_e32 v221, 0xbfb8aa3b, v221
	v_mul_f32_e32 v222, 0xbfb8aa3b, v222
	v_mul_f32_e32 v223, 0xbfb8aa3b, v223
	v_mul_f32_e32 v224, 0xbfb8aa3b, v224
	v_mul_f32_e32 v225, 0xbfb8aa3b, v225
	v_exp_f32_e32 v218, v218
	v_exp_f32_e32 v219, v219
	v_exp_f32_e32 v220, v220
	v_exp_f32_e32 v221, v221
	v_exp_f32_e32 v222, v222
	v_exp_f32_e32 v223, v223
	v_exp_f32_e32 v224, v224
	v_exp_f32_e32 v225, v225
	v_add_f32_e32 v218, 1.0, v218
	v_add_f32_e32 v219, 1.0, v219
	v_add_f32_e32 v220, 1.0, v220
	v_add_f32_e32 v221, 1.0, v221
	v_add_f32_e32 v222, 1.0, v222
	v_add_f32_e32 v223, 1.0, v223
	v_add_f32_e32 v224, 1.0, v224
	v_add_f32_e32 v225, 1.0, v225
	v_rcp_f32_e32 v218, v218
	v_rcp_f32_e32 v219, v219
	v_rcp_f32_e32 v220, v220
	v_rcp_f32_e32 v221, v221
	v_rcp_f32_e32 v222, v222
	v_rcp_f32_e32 v223, v223
	v_rcp_f32_e32 v224, v224
	v_rcp_f32_e32 v225, v225
	v_pk_mul_f32 v[30:31], v[30:31], v[218:219]
	v_pk_mul_f32 v[32:33], v[32:33], v[220:221]
	v_pk_mul_f32 v[26:27], v[26:27], v[222:223]
	v_pk_mul_f32 v[28:29], v[28:29], v[224:225]
	v_cvt_pk_bf16_f32 v130, v30, v31
	v_cvt_pk_bf16_f32 v131, v32, v33
	v_cvt_pk_bf16_f32 v132, v26, v27
	v_cvt_pk_bf16_f32 v133, v28, v29
	v_add_u32_e32 v217, 0x26c000, v216
	global_store_dwordx4 v217, v[130:133], s[94:95]
	s_waitcnt vmcnt(15)
	v_lshlrev_b32_e32 v218, 16, v134
	v_and_b32_e32 v219, 0xffff0000, v134
	v_lshlrev_b32_e32 v220, 16, v135
	v_and_b32_e32 v221, 0xffff0000, v135
	v_lshlrev_b32_e32 v222, 16, v136
	v_and_b32_e32 v223, 0xffff0000, v136
	v_lshlrev_b32_e32 v224, 16, v137
	v_and_b32_e32 v225, 0xffff0000, v137
	v_mul_f32_e32 v218, 0xbfb8aa3b, v218
	v_mul_f32_e32 v219, 0xbfb8aa3b, v219
	v_mul_f32_e32 v220, 0xbfb8aa3b, v220
	v_mul_f32_e32 v221, 0xbfb8aa3b, v221
	v_mul_f32_e32 v222, 0xbfb8aa3b, v222
	v_mul_f32_e32 v223, 0xbfb8aa3b, v223
	v_mul_f32_e32 v224, 0xbfb8aa3b, v224
	v_mul_f32_e32 v225, 0xbfb8aa3b, v225
	v_exp_f32_e32 v218, v218
	v_exp_f32_e32 v219, v219
	v_exp_f32_e32 v220, v220
	v_exp_f32_e32 v221, v221
	v_exp_f32_e32 v222, v222
	v_exp_f32_e32 v223, v223
	v_exp_f32_e32 v224, v224
	v_exp_f32_e32 v225, v225
	v_add_f32_e32 v218, 1.0, v218
	v_add_f32_e32 v219, 1.0, v219
	v_add_f32_e32 v220, 1.0, v220
	v_add_f32_e32 v221, 1.0, v221
	v_add_f32_e32 v222, 1.0, v222
	v_add_f32_e32 v223, 1.0, v223
	v_add_f32_e32 v224, 1.0, v224
	v_add_f32_e32 v225, 1.0, v225
	v_rcp_f32_e32 v218, v218
	v_rcp_f32_e32 v219, v219
	v_rcp_f32_e32 v220, v220
	v_rcp_f32_e32 v221, v221
	v_rcp_f32_e32 v222, v222
	v_rcp_f32_e32 v223, v223
	v_rcp_f32_e32 v224, v224
	v_rcp_f32_e32 v225, v225
	v_pk_mul_f32 v[22:23], v[22:23], v[218:219]
	v_pk_mul_f32 v[24:25], v[24:25], v[220:221]
	v_pk_mul_f32 v[18:19], v[18:19], v[222:223]
	v_pk_mul_f32 v[20:21], v[20:21], v[224:225]
	v_cvt_pk_bf16_f32 v134, v22, v23
	v_cvt_pk_bf16_f32 v135, v24, v25
	v_cvt_pk_bf16_f32 v136, v18, v19
	v_cvt_pk_bf16_f32 v137, v20, v21
	v_add_u32_e32 v217, 0x26c000, v216
	global_store_dwordx4 v217, v[134:137], s[94:95] offset:256
	s_waitcnt vmcnt(15)
; __device__ __forceinline__ unsigned pk2(float lo, float hi) { f32x2 v = {lo, hi}; bf16x2_t b = __builtin_convertvector(v, bf16x2_t); return __builtin_bit_cast(unsigned, b); }
; __device__ __forceinline__ float sigm(float x) { return __builtin_amdgcn_rcpf(1.f + fexp(-x)); }
; #define PG8_BAR __builtin_amdgcn_s_barrier()
; template <class Epi, bool ALIGN_EPI = true, class Sched = StaticOrder>
; __device__ __forceinline__ void gemm_phase(LAS unsigned char* lds, const Gemm g, const Sched& S, const Epi& E) {
;     ...
;         if (!has_next) break;
; #pragma unroll
;         for (int a = 0; a < 2; ++a)
; #pragma unroll
;             for (int b = 0; b < 2; ++b)
; #pragma unroll
;                 for (int m = 0; m < 4; ++m)
; #pragma unroll
;                     for (int n = 0; n < 2; ++n) acc[a][b][m][n] = (f32x4){0.f, 0.f, 0.f, 0.f};
;         cur = nxt; cA = nA; cB = nB; ++ui;
;         if constexpr (ALIGN_EPI) { if (wr == 1) PG8_BAR; }
;     __device__ __forceinline__ void operator()(const f32x4 (&acc)[2][2][4][2], const Unit& u, int wr, int wc, int fr, int fq) const {
;     ...
; #pragma unroll
;                         for (int e = 0; e < 8; ++e) o[e] = acc[ai][bj][m][e >> 2][e & 3] * sigm(ma[e]);
;                     }
;                     u32x4 w; w.x = pk2(o[0], o[1]); w.y = pk2(o[2], o[3]); w.z = pk2(o[4], o[5]); w.w = pk2(o[6], o[7]);
;                     *(u32x4*)(roww + C_MA + bj * HALF) = w;
	v_lshlrev_b32_e32 v218, 16, v148
	v_and_b32_e32 v219, 0xffff0000, v148
	v_lshlrev_b32_e32 v220, 16, v149
	v_and_b32_e32 v221, 0xffff0000, v149
	v_lshlrev_b32_e32 v222, 16, v150
	v_and_b32_e32 v223, 0xffff0000, v150
	v_lshlrev_b32_e32 v224, 16, v151
	v_and_b32_e32 v225, 0xffff0000, v151
	v_mul_f32_e32 v218, 0xbfb8aa3b, v218
	v_mul_f32_e32 v219, 0xbfb8aa3b, v219
	v_mul_f32_e32 v220, 0xbfb8aa3b, v220
	v_mul_f32_e32 v221, 0xbfb8aa3b, v221
	v_mul_f32_e32 v222, 0xbfb8aa3b, v222
	v_mul_f32_e32 v223, 0xbfb8aa3b, v223
	v_mul_f32_e32 v224, 0xbfb8aa3b, v224
	v_mul_f32_e32 v225, 0xbfb8aa3b, v225
	v_exp_f32_e32 v218, v218
	v_exp_f32_e32 v219, v219
	v_exp_f32_e32 v220, v220
	v_exp_f32_e32 v221, v221
	v_exp_f32_e32 v222, v222
	v_exp_f32_e32 v223, v223
	v_exp_f32_e32 v224, v224
	v_exp_f32_e32 v225, v225
	v_add_f32_e32 v218, 1.0, v218
	v_add_f32_e32 v219, 1.0, v219
	v_add_f32_e32 v220, 1.0, v220
	v_add_f32_e32 v221, 1.0, v221
	v_add_f32_e32 v222, 1.0, v222
	v_add_f32_e32 v223, 1.0, v223
	v_add_f32_e32 v224, 1.0, v224
	v_add_f32_e32 v225, 1.0, v225
	v_rcp_f32_e32 v218, v218
	v_rcp_f32_e32 v219, v219
	v_rcp_f32_e32 v220, v220
	v_rcp_f32_e32 v221, v221
	v_rcp_f32_e32 v222, v222
	v_rcp_f32_e32 v223, v223
	v_rcp_f32_e32 v224, v224
	v_rcp_f32_e32 v225, v225
	v_pk_mul_f32 v[14:15], v[14:15], v[218:219]
	v_pk_mul_f32 v[16:17], v[16:17], v[220:221]
	v_pk_mul_f32 v[10:11], v[10:11], v[222:223]
	v_pk_mul_f32 v[12:13], v[12:13], v[224:225]
	v_cvt_pk_bf16_f32 v148, v14, v15
	v_cvt_pk_bf16_f32 v149, v16, v17
	v_cvt_pk_bf16_f32 v150, v10, v11
	v_cvt_pk_bf16_f32 v151, v12, v13
	v_add_u32_e32 v217, 0x2aa000, v216
	global_store_dwordx4 v217, v[148:151], s[94:95]
	s_waitcnt vmcnt(15)
	v_lshlrev_b32_e32 v218, 16, v152
	v_and_b32_e32 v219, 0xffff0000, v152
	v_lshlrev_b32_e32 v220, 16, v153
	v_and_b32_e32 v221, 0xffff0000, v153
	v_lshlrev_b32_e32 v222, 16, v154
	v_and_b32_e32 v223, 0xffff0000, v154
	v_lshlrev_b32_e32 v224, 16, v155
	v_and_b32_e32 v225, 0xffff0000, v155
	v_mul_f32_e32 v218, 0xbfb8aa3b, v218
	v_mul_f32_e32 v219, 0xbfb8aa3b, v219
	v_mul_f32_e32 v220, 0xbfb8aa3b, v220
	v_mul_f32_e32 v221, 0xbfb8aa3b, v221
	v_mul_f32_e32 v222, 0xbfb8aa3b, v222
	v_mul_f32_e32 v223, 0xbfb8aa3b, v223
	v_mul_f32_e32 v224, 0xbfb8aa3b, v224
	v_mul_f32_e32 v225, 0xbfb8aa3b, v225
	v_exp_f32_e32 v218, v218
	v_exp_f32_e32 v219, v219
	v_exp_f32_e32 v220, v220
	v_exp_f32_e32 v221, v221
	v_exp_f32_e32 v222, v222
	v_exp_f32_e32 v223, v223
	v_exp_f32_e32 v224, v224
	v_exp_f32_e32 v225, v225
	v_add_f32_e32 v218, 1.0, v218
	v_add_f32_e32 v219, 1.0, v219
	v_add_f32_e32 v220, 1.0, v220
	v_add_f32_e32 v221, 1.0, v221
	v_add_f32_e32 v222, 1.0, v222
	v_add_f32_e32 v223, 1.0, v223
	v_add_f32_e32 v224, 1.0, v224
	v_add_f32_e32 v225, 1.0, v225
	v_rcp_f32_e32 v218, v218
	v_rcp_f32_e32 v219, v219
	v_rcp_f32_e32 v220, v220
	v_rcp_f32_e32 v221, v221
	v_rcp_f32_e32 v222, v222
	v_rcp_f32_e32 v223, v223
	v_rcp_f32_e32 v224, v224
	v_rcp_f32_e32 v225, v225
	v_pk_mul_f32 v[6:7], v[6:7], v[218:219]
	v_pk_mul_f32 v[8:9], v[8:9], v[220:221]
	v_pk_mul_f32 v[2:3], v[2:3], v[222:223]
	v_pk_mul_f32 v[4:5], v[4:5], v[224:225]
	v_cvt_pk_bf16_f32 v152, v6, v7
	v_cvt_pk_bf16_f32 v153, v8, v9
	v_cvt_pk_bf16_f32 v154, v2, v3
	v_cvt_pk_bf16_f32 v155, v4, v5
	v_add_u32_e32 v217, 0x2aa000, v216
	global_store_dwordx4 v217, v[152:155], s[94:95] offset:256
.LBB0_49:
	s_andn2_b64 vcc, exec, s[4:5]
	s_mov_b64 s[2:3], -1
	s_cbranch_vccnz .LBB0_31
	s_andn2_b64 vcc, exec, s[56:57]
	s_cbranch_vccnz .LBB0_30
	s_barrier
	s_branch .LBB0_30
.LBB0_53:
	s_mov_b64 s[34:35], -1
